# scan: decay folded into per-8-step cumulative scaling by the producer waves; consumer skips the S*w multiply and the w vector loads
# speedup vs baseline: 1.0232x; 1.0020x over previous
; DI float bf2f(u16 b) { return __uint_as_float(((unsigned)b) << 16); }
; DI int steprow(int b, int dir, int s) {
;     if (s < CTX) return b * CTX + (dir ? (CTX - 1 - s) : s);
;     const int t = s - CTX; return NCT + b * SEQ + (dir ? (SEQ - 1 - t) : t);
; }
; DI void scan_item(PP p, int l, int item, LAS unsigned char* lds) {
;     ...
;     auto gl = [&](int c) {
;         const int pw = wid - 4;
;         const int row0 = steprow(b, dir, c * T + pw * 8); const int rs = dir ? -1 : 1;
; #pragma unroll
;         for (int i = 0; i < 8; ++i) { const size_t o = (size_t)(row0 + rs * i) * 512 + ch;
;             pr_[i] = bf2f(RKV[o]); pk_[i] = bf2f(RKV[(size_t)NTOK * 512 + o]); pv_[i] = bf2f(RKV[(size_t)2 * NTOK * 512 + o]); pd_[i] = DEC[o]; pa_[i] = bf2f(AA[o]); }
;     };
.LBB0_245:
	s_ashr_i32 s51, s50, 31
	s_lshl_b64 s[30:31], s[50:51], 9
	s_cmp_eq_u32 s8, 0
	s_cselect_b64 s[46:47], -1, 0
	v_or_b32_e32 v6, s30, v96
	v_mov_b32_e32 v7, s31
	s_and_b64 s[30:31], s[46:47], exec
	s_waitcnt vmcnt(7)
	v_lshlrev_b64 v[8:9], 1, v[6:7]
	s_cselect_b32 s58, 1, -1
	v_lshl_add_u64 v[4:5], s[4:5], 0, v[8:9]
	s_mov_b32 s7, 0x1200000
	s_cselect_b32 s57, 2, -2
	s_cselect_b32 s56, 3, -3
	s_cselect_b32 s55, 4, -4
	s_cselect_b32 s54, 5, -5
	s_cselect_b32 s31, 6, -6
	s_cselect_b32 s30, 7, -7
	s_add_i32 s60, s50, s58
	v_add_co_u32_e32 v10, vcc, s7, v4
	s_ashr_i32 s61, s60, 31
	s_nop 0
	v_addc_co_u32_e32 v11, vcc, 0, v5, vcc
	s_lshl_b64 s[60:61], s[60:61], 9
	global_load_ushort v2, v[4:5], off
	global_load_ushort v3, v[10:11], off
	s_mov_b32 s3, 0x2400000
	v_or_b32_e32 v10, s60, v96
	v_mov_b32_e32 v11, s61
	v_add_co_u32_e32 v4, vcc, s3, v4
	s_waitcnt vmcnt(8)
	v_lshlrev_b64 v[12:13], 1, v[10:11]
	v_addc_co_u32_e32 v5, vcc, 0, v5, vcc
	v_lshl_add_u64 v[6:7], v[6:7], 2, s[36:37]
	v_lshl_add_u64 v[14:15], s[4:5], 0, v[12:13]
	v_lshl_add_u64 v[10:11], v[10:11], 2, s[36:37]
	v_lshl_add_u64 v[12:13], s[42:43], 0, v[12:13]
	s_add_i32 s60, s50, s57
	global_load_ushort v4, v[4:5], off
	s_ashr_i32 s61, s60, 31
	global_load_dword v10, v[10:11], off
	s_lshl_b64 s[60:61], s[60:61], 9
	global_load_dword v5, v[6:7], off
	global_load_ushort v11, v[12:13], off
	v_lshl_add_u64 v[6:7], s[42:43], 0, v[8:9]
	v_add_co_u32_e32 v8, vcc, s7, v14
	global_load_ushort v6, v[6:7], off
	s_nop 0
	v_addc_co_u32_e32 v9, vcc, 0, v15, vcc
	global_load_ushort v8, v[8:9], off
	s_waitcnt vmcnt(13)
	v_or_b32_e32 v16, s60, v96
	global_load_ushort v7, v[14:15], off
	v_add_co_u32_e32 v14, vcc, s3, v14
	v_mov_b32_e32 v17, s61
	s_nop 0
	v_addc_co_u32_e32 v15, vcc, 0, v15, vcc
	v_lshlrev_b64 v[18:19], 1, v[16:17]
	global_load_ushort v9, v[14:15], off
	v_lshl_add_u64 v[14:15], s[4:5], 0, v[18:19]
	s_add_i32 s60, s50, s56
	s_waitcnt vmcnt(13)
	v_add_co_u32_e32 v20, vcc, s7, v14
	s_ashr_i32 s61, s60, 31
	s_nop 0
	v_addc_co_u32_e32 v21, vcc, 0, v15, vcc
	s_lshl_b64 s[60:61], s[60:61], 9
	global_load_ushort v12, v[14:15], off
	global_load_ushort v13, v[20:21], off
	v_or_b32_e32 v20, s60, v96
	v_mov_b32_e32 v21, s61
	v_add_co_u32_e32 v14, vcc, s3, v14
	v_lshlrev_b64 v[22:23], 1, v[20:21]
	s_nop 0
	v_addc_co_u32_e32 v15, vcc, 0, v15, vcc
	v_lshl_add_u64 v[16:17], v[16:17], 2, s[36:37]
	v_lshl_add_u64 v[24:25], s[4:5], 0, v[22:23]
	v_lshl_add_u64 v[20:21], v[20:21], 2, s[36:37]
	v_lshl_add_u64 v[22:23], s[42:43], 0, v[22:23]
	s_add_i32 s60, s50, s55
	global_load_ushort v14, v[14:15], off
	s_ashr_i32 s61, s60, 31
	global_load_dword v20, v[20:21], off
	s_lshl_b64 s[60:61], s[60:61], 9
	global_load_dword v15, v[16:17], off
	global_load_ushort v21, v[22:23], off
	v_lshl_add_u64 v[16:17], s[42:43], 0, v[18:19]
	v_add_co_u32_e32 v18, vcc, s7, v24
	global_load_ushort v16, v[16:17], off
	s_nop 0
	v_addc_co_u32_e32 v19, vcc, 0, v25, vcc
	global_load_ushort v18, v[18:19], off
	v_or_b32_e32 v26, s60, v96
	global_load_ushort v17, v[24:25], off
	v_add_co_u32_e32 v24, vcc, s3, v24
	v_mov_b32_e32 v27, s61
	s_nop 0
	v_addc_co_u32_e32 v25, vcc, 0, v25, vcc
	s_waitcnt vmcnt(21)
	v_lshlrev_b64 v[28:29], 1, v[26:27]
	global_load_ushort v19, v[24:25], off
	v_lshl_add_u64 v[24:25], s[4:5], 0, v[28:29]
	s_add_i32 s60, s50, s54
	v_add_co_u32_e32 v30, vcc, s7, v24
	s_ashr_i32 s61, s60, 31
	s_nop 0
	v_addc_co_u32_e32 v31, vcc, 0, v25, vcc
	s_lshl_b64 s[60:61], s[60:61], 9
	global_load_ushort v22, v[24:25], off
	global_load_ushort v23, v[30:31], off
	v_or_b32_e32 v30, s60, v96
	v_mov_b32_e32 v31, s61
	v_add_co_u32_e32 v24, vcc, s3, v24
	v_lshlrev_b64 v[32:33], 1, v[30:31]
	s_nop 0
	v_addc_co_u32_e32 v25, vcc, 0, v25, vcc
	v_lshl_add_u64 v[26:27], v[26:27], 2, s[36:37]
	v_lshl_add_u64 v[34:35], s[4:5], 0, v[32:33]
	v_lshl_add_u64 v[30:31], v[30:31], 2, s[36:37]
	v_lshl_add_u64 v[32:33], s[42:43], 0, v[32:33]
	s_add_i32 s60, s50, s31
	global_load_ushort v24, v[24:25], off
	s_ashr_i32 s61, s60, 31
	global_load_dword v30, v[30:31], off
	s_lshl_b64 s[60:61], s[60:61], 9
	global_load_dword v25, v[26:27], off
	global_load_ushort v31, v[32:33], off
	v_lshl_add_u64 v[26:27], s[42:43], 0, v[28:29]
	v_add_co_u32_e32 v28, vcc, s7, v34
	global_load_ushort v26, v[26:27], off
	s_nop 0
	v_addc_co_u32_e32 v29, vcc, 0, v35, vcc
	global_load_ushort v28, v[28:29], off
	v_or_b32_e32 v36, s60, v96
	global_load_ushort v27, v[34:35], off
	v_add_co_u32_e32 v34, vcc, s3, v34
	v_mov_b32_e32 v37, s61
	s_nop 0
	v_addc_co_u32_e32 v35, vcc, 0, v35, vcc
	v_lshlrev_b64 v[38:39], 1, v[36:37]
	global_load_ushort v29, v[34:35], off
	v_lshl_add_u64 v[34:35], s[4:5], 0, v[38:39]
	s_add_i32 s50, s50, s30
	v_add_co_u32_e32 v40, vcc, s7, v34
	s_ashr_i32 s51, s50, 31
	s_nop 0
	v_addc_co_u32_e32 v41, vcc, 0, v35, vcc
	s_lshl_b64 s[50:51], s[50:51], 9
	global_load_ushort v32, v[34:35], off
	global_load_ushort v33, v[40:41], off
	v_or_b32_e32 v40, s50, v96
	v_mov_b32_e32 v41, s51
	v_add_co_u32_e32 v34, vcc, s3, v34
	v_lshlrev_b64 v[42:43], 1, v[40:41]
	s_nop 0
	v_addc_co_u32_e32 v35, vcc, 0, v35, vcc
	v_lshl_add_u64 v[36:37], v[36:37], 2, s[36:37]
	v_lshl_add_u64 v[44:45], s[4:5], 0, v[42:43]
	v_lshl_add_u64 v[40:41], v[40:41], 2, s[36:37]
	v_lshl_add_u64 v[42:43], s[42:43], 0, v[42:43]
	global_load_ushort v34, v[34:35], off
	s_waitcnt vmcnt(31)
; DI void scan_item(PP p, int l, int item, LAS unsigned char* lds) {
;     ...
;     auto fill = [&](int c) {
;         const int pw = wid - 4;
;         float kk[8], n2[8];
; #pragma unroll
;         for (int i = 0; i < 8; ++i) { kk[i] = pk_[i] * kkw; n2[i] = kk[i] * kk[i]; }
; #pragma unroll
;         for (int i = 0; i < 8; ++i) n2[i] += dpp_f(n2[i], 0);
; #pragma unroll
;         for (int i = 0; i < 8; ++i) n2[i] += dpp_f(n2[i], 1);
; #pragma unroll
;         for (int i = 0; i < 8; ++i) n2[i] += dpp_f(n2[i], 2);
; #pragma unroll
;         for (int i = 0; i < 8; ++i) n2[i] += dpp_f(n2[i], 3);
; #pragma unroll
;         for (int i = 0; i < 8; ++i) n2[i] += __shfl_xor(n2[i], 16);
	v_lshlrev_b32_e32 v3, 16, v3
	global_load_dword v40, v[40:41], off
	v_and_b32_e32 v59, 64, v185
	global_load_dword v35, v[36:37], off
	global_load_ushort v41, v[42:43], off
	v_lshl_add_u64 v[36:37], s[42:43], 0, v[38:39]
	v_add_co_u32_e32 v38, vcc, s7, v44
	global_load_ushort v36, v[36:37], off
	s_nop 0
	v_addc_co_u32_e32 v39, vcc, 0, v45, vcc
	global_load_ushort v38, v[38:39], off
	v_mul_f32_e32 v42, v117, v3
	v_mul_f32_e32 v43, v42, v42
	global_load_ushort v37, v[44:45], off
	v_add_co_u32_e32 v44, vcc, s3, v44
	v_mov_b32_dpp v43, v43 quad_perm:[1,0,3,2] row_mask:0xf bank_mask:0xf bound_ctrl:1
	s_nop 0
	v_addc_co_u32_e32 v45, vcc, 0, v45, vcc
	v_fmac_f32_e32 v43, v42, v42
	v_xor_b32_e32 v58, 16, v185
	v_add_u32_e32 v59, 64, v59
	s_waitcnt vmcnt(31)
	v_lshlrev_b32_e32 v8, 16, v8
	v_add_f32_dpp v43, v43, v43 quad_perm:[2,3,0,1] row_mask:0xf bank_mask:0xf bound_ctrl:1
	v_cmp_lt_i32_e32 vcc, v58, v59
	global_load_ushort v39, v[44:45], off
	v_mul_f32_e32 v44, v117, v8
	v_add_f32_dpp v43, v43, v43 row_half_mirror row_mask:0xf bank_mask:0xf bound_ctrl:1
	v_cndmask_b32_e32 v58, v185, v58, vcc
	v_mul_f32_e32 v45, v44, v44
	v_add_f32_dpp v43, v43, v43 row_mirror row_mask:0xf bank_mask:0xf bound_ctrl:1
	v_lshlrev_b32_e32 v58, 2, v58
	v_mov_b32_dpp v45, v45 quad_perm:[1,0,3,2] row_mask:0xf bank_mask:0xf bound_ctrl:1
	ds_bpermute_b32 v60, v58, v43
	v_fmac_f32_e32 v45, v44, v44
	s_waitcnt vmcnt(28)
	v_lshlrev_b32_e32 v13, 16, v13
	v_mul_f32_e32 v46, v117, v13
	v_add_f32_dpp v45, v45, v45 quad_perm:[2,3,0,1] row_mask:0xf bank_mask:0xf bound_ctrl:1
	v_mul_f32_e32 v47, v46, v46
	s_waitcnt lgkmcnt(0)
	v_add_f32_e32 v43, v43, v60
	v_add_f32_dpp v45, v45, v45 row_half_mirror row_mask:0xf bank_mask:0xf bound_ctrl:1
	v_mov_b32_dpp v47, v47 quad_perm:[1,0,3,2] row_mask:0xf bank_mask:0xf bound_ctrl:1
	v_fmac_f32_e32 v47, v46, v46
	v_add_f32_dpp v45, v45, v45 row_mirror row_mask:0xf bank_mask:0xf bound_ctrl:1
	ds_bpermute_b32 v60, v58, v45
	s_waitcnt vmcnt(22)
	v_lshlrev_b32_e32 v18, 16, v18
	v_add_f32_dpp v47, v47, v47 quad_perm:[2,3,0,1] row_mask:0xf bank_mask:0xf bound_ctrl:1
	v_mul_f32_e32 v48, v117, v18
	v_mul_f32_e32 v49, v48, v48
	v_add_f32_dpp v47, v47, v47 row_half_mirror row_mask:0xf bank_mask:0xf bound_ctrl:1
	s_waitcnt lgkmcnt(0)
	v_add_f32_e32 v45, v45, v60
	v_mov_b32_dpp v49, v49 quad_perm:[1,0,3,2] row_mask:0xf bank_mask:0xf bound_ctrl:1
	v_add_f32_dpp v47, v47, v47 row_mirror row_mask:0xf bank_mask:0xf bound_ctrl:1
	ds_bpermute_b32 v60, v58, v47
	v_fmac_f32_e32 v49, v48, v48
	s_waitcnt vmcnt(18)
	v_lshlrev_b32_e32 v23, 16, v23
	v_mul_f32_e32 v50, v117, v23
	v_add_f32_dpp v49, v49, v49 quad_perm:[2,3,0,1] row_mask:0xf bank_mask:0xf bound_ctrl:1
	v_mul_f32_e32 v51, v50, v50
	s_waitcnt lgkmcnt(0)
	v_add_f32_e32 v47, v47, v60
	v_add_f32_dpp v49, v49, v49 row_half_mirror row_mask:0xf bank_mask:0xf bound_ctrl:1
	v_mov_b32_dpp v51, v51 quad_perm:[1,0,3,2] row_mask:0xf bank_mask:0xf bound_ctrl:1
	v_fmac_f32_e32 v51, v50, v50
	v_add_f32_dpp v49, v49, v49 row_mirror row_mask:0xf bank_mask:0xf bound_ctrl:1
	ds_bpermute_b32 v60, v58, v49
	s_waitcnt vmcnt(12)
	v_lshlrev_b32_e32 v28, 16, v28
	v_add_f32_dpp v51, v51, v51 quad_perm:[2,3,0,1] row_mask:0xf bank_mask:0xf bound_ctrl:1
	v_mul_f32_e32 v52, v117, v28
	v_mul_f32_e32 v53, v52, v52
	v_add_f32_dpp v51, v51, v51 row_half_mirror row_mask:0xf bank_mask:0xf bound_ctrl:1
	s_waitcnt lgkmcnt(0)
	v_add_f32_e32 v49, v49, v60
	v_mov_b32_dpp v53, v53 quad_perm:[1,0,3,2] row_mask:0xf bank_mask:0xf bound_ctrl:1
	v_add_f32_dpp v51, v51, v51 row_mirror row_mask:0xf bank_mask:0xf bound_ctrl:1
	ds_bpermute_b32 v60, v58, v51
	v_fmac_f32_e32 v53, v52, v52
	s_waitcnt vmcnt(8)
	v_lshlrev_b32_e32 v33, 16, v33
	v_mul_f32_e32 v54, v117, v33
	v_add_f32_dpp v53, v53, v53 quad_perm:[2,3,0,1] row_mask:0xf bank_mask:0xf bound_ctrl:1
	v_mul_f32_e32 v55, v54, v54
	s_waitcnt lgkmcnt(0)
	v_add_f32_e32 v51, v51, v60
	v_add_f32_dpp v53, v53, v53 row_half_mirror row_mask:0xf bank_mask:0xf bound_ctrl:1
	v_mov_b32_dpp v55, v55 quad_perm:[1,0,3,2] row_mask:0xf bank_mask:0xf bound_ctrl:1
	v_fmac_f32_e32 v55, v54, v54
	v_add_f32_dpp v53, v53, v53 row_mirror row_mask:0xf bank_mask:0xf bound_ctrl:1
	ds_bpermute_b32 v60, v58, v53
	v_add_f32_dpp v55, v55, v55 quad_perm:[2,3,0,1] row_mask:0xf bank_mask:0xf bound_ctrl:1
	s_mulk_i32 s6, 0x600
	s_add_i32 s6, s6, 0
	v_add_f32_dpp v55, v55, v55 row_half_mirror row_mask:0xf bank_mask:0xf bound_ctrl:1
	s_waitcnt lgkmcnt(0)
	v_add_f32_e32 v53, v53, v60
	s_waitcnt vmcnt(2)
	v_lshlrev_b32_e32 v38, 16, v38
	v_mul_f32_e32 v56, v117, v38
	v_mul_f32_e32 v57, v56, v56
	v_add_f32_dpp v55, v55, v55 row_mirror row_mask:0xf bank_mask:0xf bound_ctrl:1
	ds_bpermute_b32 v60, v58, v55
	v_mov_b32_dpp v57, v57 quad_perm:[1,0,3,2] row_mask:0xf bank_mask:0xf bound_ctrl:1
	v_fmac_f32_e32 v57, v56, v56
	v_lshlrev_b32_e32 v2, 16, v2
	v_lshlrev_b32_e32 v6, 16, v6
	v_add_f32_dpp v57, v57, v57 quad_perm:[2,3,0,1] row_mask:0xf bank_mask:0xf bound_ctrl:1
	s_waitcnt lgkmcnt(0)
	v_add_f32_e32 v55, v55, v60
	v_lshlrev_b32_e32 v4, 16, v4
	v_add_f32_dpp v57, v57, v57 row_half_mirror row_mask:0xf bank_mask:0xf bound_ctrl:1
	v_lshlrev_b32_e32 v11, 16, v11
	v_lshlrev_b32_e32 v9, 16, v9
	v_add_f32_dpp v57, v57, v57 row_mirror row_mask:0xf bank_mask:0xf bound_ctrl:1
	ds_bpermute_b32 v58, v58, v57
	v_lshlrev_b32_e32 v16, 16, v16
	v_lshlrev_b32_e32 v14, 16, v14
	v_lshlrev_b32_e32 v21, 16, v21
	v_lshlrev_b32_e32 v19, 16, v19
	s_waitcnt lgkmcnt(0)
; #define LAS __attribute__((address_space(3)))
; DI void scan_item(PP p, int l, int item, LAS unsigned char* lds) {
;     ...
;         for (int i = 0; i < 8; ++i) n2[i] += __shfl_xor(n2[i], 16);
; #pragma unroll
;         for (int i = 0; i < 8; ++i) n2[i] += __shfl_xor(n2[i], 32);
; #pragma unroll
;         for (int i = 0; i < 8; ++i) {
;             const float kn = kk[i] * __builtin_amdgcn_rsqf(fmaxf(n2[i], 1e-24f));
;             LAS float* d = buf + ((c & 1) * T + pw * 8 + i) * 384 + lane;
;             d[0] = pr_[i]; d[64] = pd_[i]; d[128] = pk_[i] * (1.0f + (pa_[i] - 1.0f) * kaw); d[192] = -kn; d[256] = kn * pa_[i]; d[320] = pv_[i];
;         }
	v_add_f32_e32 v57, v57, v58
	v_xor_b32_e32 v58, 32, v185
	v_cmp_lt_i32_e32 vcc, v58, v59
	v_lshlrev_b32_e32 v26, 16, v26
	v_lshlrev_b32_e32 v24, 16, v24
	v_cndmask_b32_e32 v58, v185, v58, vcc
	v_lshlrev_b32_e32 v58, 2, v58
	ds_bpermute_b32 v59, v58, v43
	v_lshlrev_b32_e32 v31, 16, v31
	v_lshlrev_b32_e32 v29, 16, v29
	v_lshlrev_b32_e32 v36, 16, v36
	v_lshlrev_b32_e32 v34, 16, v34
	s_waitcnt lgkmcnt(0)
	v_add_f32_e32 v43, v43, v59
	ds_bpermute_b32 v59, v58, v45
	v_max_f32_e32 v43, 0x179abe15, v43
	v_rsq_f32_e32 v43, v43
	v_lshlrev_b32_e32 v41, 16, v41
	v_lshlrev_b32_e32 v7, 16, v7
	s_waitcnt lgkmcnt(0)
	v_add_f32_e32 v45, v45, v59
	ds_bpermute_b32 v59, v58, v47
	v_lshlrev_b32_e32 v12, 16, v12
	v_lshlrev_b32_e32 v17, 16, v17
	v_lshlrev_b32_e32 v22, 16, v22
	v_lshlrev_b32_e32 v27, 16, v27
	s_waitcnt lgkmcnt(0)
	v_add_f32_e32 v47, v47, v59
	ds_bpermute_b32 v59, v58, v49
	v_lshlrev_b32_e32 v32, 16, v32
	s_waitcnt vmcnt(1)
	v_lshlrev_b32_e32 v37, 16, v37
	s_waitcnt vmcnt(0)
	v_lshlrev_b32_e32 v39, 16, v39
	s_cmp_gt_u32 s41, 31
	s_waitcnt lgkmcnt(0)
	v_add_f32_e32 v49, v49, v59
	ds_bpermute_b32 v59, v58, v51
	s_waitcnt lgkmcnt(0)
	v_add_f32_e32 v51, v51, v59
	ds_bpermute_b32 v59, v58, v53
	s_waitcnt lgkmcnt(0)
	v_add_f32_e32 v53, v53, v59
	ds_bpermute_b32 v59, v58, v55
	ds_bpermute_b32 v58, v58, v57
	s_waitcnt lgkmcnt(1)
	v_add_f32_e32 v55, v55, v59
	s_waitcnt lgkmcnt(0)
	v_add_f32_e32 v57, v57, v58
	v_lshl_add_u32 v58, v1, 2, s6
	ds_write2st64_b32 v58, v2, v5 offset1:1
	v_add_f32_e32 v2, -1.0, v6
	v_fma_f32 v2, v129, v2, 1.0
	v_mul_f32_e32 v2, v2, v3
	v_mul_f32_e64 v3, v42, -v43
	ds_write2st64_b32 v58, v2, v3 offset0:2 offset1:3
	v_mul_f32_e64 v2, -v3, v6
	ds_write2st64_b32 v58, v2, v4 offset0:4 offset1:5
	v_max_f32_e32 v2, 0x179abe15, v45
	v_rsq_f32_e32 v2, v2
	v_add_f32_e32 v3, -1.0, v11
	v_fma_f32 v3, v129, v3, 1.0
	v_mul_f32_e32 v3, v3, v8
	v_mul_f32_e64 v2, v44, -v2
	ds_write2st64_b32 v58, v3, v2 offset0:8 offset1:9
	v_mul_f32_e64 v2, -v2, v11
	ds_write2st64_b32 v58, v2, v9 offset0:10 offset1:11
	v_max_f32_e32 v2, 0x179abe15, v47
	v_rsq_f32_e32 v2, v2
	v_add_f32_e32 v3, -1.0, v16
	v_fma_f32 v3, v129, v3, 1.0
	v_mul_f32_e32 v3, v3, v13
	v_mul_f32_e64 v2, v46, -v2
	ds_write2st64_b32 v58, v3, v2 offset0:14 offset1:15
	v_mul_f32_e64 v2, -v2, v16
	ds_write2st64_b32 v58, v2, v14 offset0:16 offset1:17
	v_max_f32_e32 v2, 0x179abe15, v49
	v_rsq_f32_e32 v2, v2
	v_add_f32_e32 v3, -1.0, v21
	v_fma_f32 v3, v129, v3, 1.0
	v_mul_f32_e32 v3, v3, v18
	v_mul_f32_e64 v2, v48, -v2
	ds_write2st64_b32 v58, v3, v2 offset0:20 offset1:21
	v_mul_f32_e64 v2, -v2, v21
	ds_write2st64_b32 v58, v2, v19 offset0:22 offset1:23
	v_max_f32_e32 v2, 0x179abe15, v51
	v_rsq_f32_e32 v2, v2
	v_add_f32_e32 v3, -1.0, v26
	v_fma_f32 v3, v129, v3, 1.0
	v_mul_f32_e32 v3, v3, v23
	v_mul_f32_e64 v2, v50, -v2
	ds_write2st64_b32 v58, v3, v2 offset0:26 offset1:27
	v_mul_f32_e64 v2, -v2, v26
	ds_write2st64_b32 v58, v2, v24 offset0:28 offset1:29
	v_max_f32_e32 v2, 0x179abe15, v53
	v_rsq_f32_e32 v2, v2
	v_add_f32_e32 v3, -1.0, v31
	v_fma_f32 v3, v129, v3, 1.0
	v_mul_f32_e32 v3, v3, v28
	v_mul_f32_e64 v2, v52, -v2
	ds_write2st64_b32 v58, v3, v2 offset0:32 offset1:33
	v_mul_f32_e64 v2, -v2, v31
	ds_write2st64_b32 v58, v2, v29 offset0:34 offset1:35
	v_max_f32_e32 v2, 0x179abe15, v55
	v_rsq_f32_e32 v2, v2
	v_add_f32_e32 v3, -1.0, v36
	v_fma_f32 v3, v129, v3, 1.0
	v_mul_f32_e32 v3, v3, v33
	v_mul_f32_e64 v2, v54, -v2
	ds_write2st64_b32 v58, v3, v2 offset0:38 offset1:39
	v_mul_f32_e64 v2, -v2, v36
	ds_write2st64_b32 v58, v2, v34 offset0:40 offset1:41
	v_max_f32_e32 v2, 0x179abe15, v57
	v_rsq_f32_e32 v2, v2
	v_add_f32_e32 v3, -1.0, v41
	v_fma_f32 v3, v129, v3, 1.0
	v_mul_f32_e32 v3, v3, v38
	v_mul_f32_e64 v2, v56, -v2
	ds_write2st64_b32 v58, v3, v2 offset0:44 offset1:45
	v_mul_f32_e64 v2, -v2, v41
	s_mov_b64 s[6:7], -1
	ds_write2st64_b32 v58, v7, v10 offset0:6 offset1:7
	ds_write2st64_b32 v58, v12, v15 offset0:12 offset1:13
	ds_write2st64_b32 v58, v17, v20 offset0:18 offset1:19
	ds_write2st64_b32 v58, v22, v25 offset0:24 offset1:25
	ds_write2st64_b32 v58, v27, v30 offset0:30 offset1:31
	ds_write2st64_b32 v58, v32, v35 offset0:36 offset1:37
	ds_write2st64_b32 v58, v37, v40 offset0:42 offset1:43
	ds_write2st64_b32 v58, v2, v39 offset0:46 offset1:47
	v_mov_b32_e32 v153, 1.0
	ds_read_b32 v118, v58 offset:0
	ds_read_b32 v122, v58 offset:256
	ds_read_b32 v126, v58 offset:512
	ds_read_b32 v144, v58 offset:768
	ds_read_b32 v148, v58 offset:1024
	ds_read_b32 v119, v58 offset:1536
	ds_read_b32 v123, v58 offset:1792
	ds_read_b32 v127, v58 offset:2048
	ds_read_b32 v145, v58 offset:2304
	ds_read_b32 v149, v58 offset:2560
	ds_read_b32 v120, v58 offset:3072
	ds_read_b32 v124, v58 offset:3328
	ds_read_b32 v128, v58 offset:3584
	ds_read_b32 v146, v58 offset:3840
	ds_read_b32 v150, v58 offset:4096
	ds_read_b32 v121, v58 offset:4608
	ds_read_b32 v125, v58 offset:4864
	ds_read_b32 v116, v58 offset:5120
	ds_read_b32 v147, v58 offset:5376
	ds_read_b32 v151, v58 offset:5632
	s_waitcnt lgkmcnt(0)
; #define LAS __attribute__((address_space(3)))
; DI void scan_item(PP p, int l, int item, LAS unsigned char* lds) {
;     ...
;         for (int i = 0; i < 8; ++i) {
;             const float kn = kk[i] * __builtin_amdgcn_rsqf(fmaxf(n2[i], 1e-24f));
;             LAS float* d = buf + ((c & 1) * T + pw * 8 + i) * 384 + lane;
;             d[0] = pr_[i]; d[64] = pd_[i]; d[128] = pk_[i] * (1.0f + (pa_[i] - 1.0f) * kaw); d[192] = -kn; d[256] = kn * pa_[i]; d[320] = pv_[i];
;         }
	v_mul_f32_e32 v144, v144, v153
	v_mul_f32_e32 v153, v153, v122
	v_rcp_f32_e32 v154, v153
	v_mul_f32_e32 v118, v118, v153
	v_mov_b32_e32 v122, v153
	v_mul_f32_e32 v126, v126, v154
	v_mul_f32_e32 v148, v148, v154
	v_mul_f32_e32 v145, v145, v153
	v_mul_f32_e32 v153, v153, v123
	v_rcp_f32_e32 v155, v153
	v_mul_f32_e32 v119, v119, v153
	v_mov_b32_e32 v123, v153
	v_mul_f32_e32 v127, v127, v155
	v_mul_f32_e32 v149, v149, v155
	v_mul_f32_e32 v146, v146, v153
	v_mul_f32_e32 v153, v153, v124
	v_rcp_f32_e32 v156, v153
	v_mul_f32_e32 v120, v120, v153
	v_mov_b32_e32 v124, v153
	v_mul_f32_e32 v128, v128, v156
	v_mul_f32_e32 v150, v150, v156
	v_mul_f32_e32 v147, v147, v153
	v_mul_f32_e32 v153, v153, v125
	v_rcp_f32_e32 v157, v153
	v_mul_f32_e32 v121, v121, v153
	v_mov_b32_e32 v125, v153
	v_mul_f32_e32 v116, v116, v157
	v_mul_f32_e32 v151, v151, v157
	ds_write_b32 v58, v118 offset:0
	ds_write_b32 v58, v122 offset:256
	ds_write_b32 v58, v126 offset:512
	ds_write_b32 v58, v144 offset:768
	ds_write_b32 v58, v148 offset:1024
	ds_write_b32 v58, v119 offset:1536
	ds_write_b32 v58, v123 offset:1792
	ds_write_b32 v58, v127 offset:2048
	ds_write_b32 v58, v145 offset:2304
	ds_write_b32 v58, v149 offset:2560
	ds_write_b32 v58, v120 offset:3072
	ds_write_b32 v58, v124 offset:3328
	ds_write_b32 v58, v128 offset:3584
	ds_write_b32 v58, v146 offset:3840
	ds_write_b32 v58, v150 offset:4096
	ds_write_b32 v58, v121 offset:4608
	ds_write_b32 v58, v125 offset:4864
	ds_write_b32 v58, v116 offset:5120
	ds_write_b32 v58, v147 offset:5376
	ds_write_b32 v58, v151 offset:5632
	ds_read_b32 v118, v58 offset:6144
	ds_read_b32 v122, v58 offset:6400
	ds_read_b32 v126, v58 offset:6656
	ds_read_b32 v144, v58 offset:6912
	ds_read_b32 v148, v58 offset:7168
	ds_read_b32 v119, v58 offset:7680
	ds_read_b32 v123, v58 offset:7936
	ds_read_b32 v127, v58 offset:8192
	ds_read_b32 v145, v58 offset:8448
	ds_read_b32 v149, v58 offset:8704
	ds_read_b32 v120, v58 offset:9216
	ds_read_b32 v124, v58 offset:9472
	ds_read_b32 v128, v58 offset:9728
	ds_read_b32 v146, v58 offset:9984
	ds_read_b32 v150, v58 offset:10240
	ds_read_b32 v121, v58 offset:10752
	ds_read_b32 v125, v58 offset:11008
	ds_read_b32 v116, v58 offset:11264
	ds_read_b32 v147, v58 offset:11520
	ds_read_b32 v151, v58 offset:11776
	s_waitcnt lgkmcnt(0)
	v_mul_f32_e32 v144, v144, v153
	v_mul_f32_e32 v153, v153, v122
	v_rcp_f32_e32 v154, v153
	v_mul_f32_e32 v118, v118, v153
	v_mov_b32_e32 v122, v153
	v_mul_f32_e32 v126, v126, v154
	v_mul_f32_e32 v148, v148, v154
	v_mul_f32_e32 v145, v145, v153
	v_mul_f32_e32 v153, v153, v123
	v_rcp_f32_e32 v155, v153
	v_mul_f32_e32 v119, v119, v153
	v_mov_b32_e32 v123, v153
	v_mul_f32_e32 v127, v127, v155
	v_mul_f32_e32 v149, v149, v155
	v_mul_f32_e32 v146, v146, v153
	v_mul_f32_e32 v153, v153, v124
	v_rcp_f32_e32 v156, v153
	v_mul_f32_e32 v120, v120, v153
	v_mov_b32_e32 v124, v153
	v_mul_f32_e32 v128, v128, v156
	v_mul_f32_e32 v150, v150, v156
	v_mul_f32_e32 v147, v147, v153
	v_mul_f32_e32 v153, v153, v125
	v_rcp_f32_e32 v157, v153
	v_mul_f32_e32 v121, v121, v153
	v_mov_b32_e32 v125, v153
	v_mul_f32_e32 v116, v116, v157
	v_mul_f32_e32 v151, v151, v157
	ds_write_b32 v58, v118 offset:6144
	ds_write_b32 v58, v122 offset:6400
	ds_write_b32 v58, v126 offset:6656
	ds_write_b32 v58, v144 offset:6912
	ds_write_b32 v58, v148 offset:7168
	ds_write_b32 v58, v119 offset:7680
	ds_write_b32 v58, v123 offset:7936
	ds_write_b32 v58, v127 offset:8192
	ds_write_b32 v58, v145 offset:8448
	ds_write_b32 v58, v149 offset:8704
	ds_write_b32 v58, v120 offset:9216
	ds_write_b32 v58, v124 offset:9472
	ds_write_b32 v58, v128 offset:9728
	ds_write_b32 v58, v146 offset:9984
	ds_write_b32 v58, v150 offset:10240
	ds_write_b32 v58, v121 offset:10752
	ds_write_b32 v58, v125 offset:11008
	ds_write_b32 v58, v116 offset:11264
	ds_write_b32 v58, v147 offset:11520
	ds_write_b32 v58, v151 offset:11776
	s_cbranch_scc0 .LBB0_247
	s_add_i32 s50, s52, 0xffffff00
	s_lshl_b32 s51, s24, 11
	s_sub_i32 s59, 0x8ff, s52
	s_and_b64 s[6:7], s[46:47], exec
	s_cselect_b32 s6, s50, s59
	s_add_i32 s6, s51, s6
	s_add_i32 s50, s6, 0x800
	s_mov_b64 s[6:7], 0

; #define LAS __attribute__((address_space(3)))
; DI void scan_item(PP p, int l, int item, LAS unsigned char* lds) {
;     ...
;         else {
;             const LAS float* sp = buf + ((c & 1) * T) * 384;
;             f32x4 Ar0, Ar1, Aw0, Aw1, Ak0, Ak1, Aa0, Aa1, Ab0, Ab1; float Avv;
;             f32x4 Br0, Br1, Bw0, Bw1, Bk0, Bk1, Ba0, Ba1, Bb0, Bb1; float Bvv;
;             SC_LD(A, sp);
;             const ptrdiff_t ystep = dir ? -512 : 512;
;             u16* Yl = Yp + (size_t)steprow(b, dir, c * T) * 512 + (ptrdiff_t)ks * ystep;
; #pragma nounroll
;             for (int st = 0; st < T; st += 2) {
;                 SC_LD(B, sp + (st + 1) * 384);
.LBB0_253:
	s_mov_b64 s[6:7], -1
	s_and_b64 vcc, exec, s[44:45]
	s_cbranch_vccz .LBB0_265
	s_setprio 3
	s_lshl_b32 s7, s30, 5
	s_and_b32 s6, s7, 32
	s_mulk_i32 s6, 0x600
	v_lshl_add_u32 v154, v138, 2, s6
	v_lshl_add_u32 v153, v136, 2, s6
	ds_read_b128 v[0:3], v154 offset:0
	ds_read_b128 v[4:7], v154 offset:16
	ds_read_b128 v[24:27], v154 offset:768
	ds_read_b128 v[28:31], v154 offset:784
	ds_read_b128 v[16:19], v154 offset:512
	ds_read_b128 v[20:23], v154 offset:528
	ds_read_b128 v[32:35], v154 offset:1024
	ds_read_b128 v[36:39], v154 offset:1040
	ds_read_b32 v116, v153 offset:1280
	s_cmp_gt_u32 s30, 7
	s_cbranch_scc0 .Lscan_ctx_rows
	s_add_i32 s6, s7, 0xffffff00
	s_sub_i32 s68, 0x8ff, s7
	s_and_b64 s[8:9], s[46:47], exec
	s_cselect_b32 s6, s6, s68
	s_add_i32 s6, s6, s53
	s_branch .Lscan_row_done

; DI void scan_item(PP p, int l, int item, LAS unsigned char* lds) {
;     ...
;             u16* Yl = Yp + (size_t)steprow(b, dir, c * T) * 512 + (ptrdiff_t)ks * ystep;
; #pragma nounroll
;             for (int st = 0; st < T; st += 2) {
;                 SC_LD(B, sp + (st + 1) * 384);
;                 SC_STEP(A, st);
;                 if (st + 2 < T) SC_LD(A, sp + (st + 2) * 384);
.Lscan_row_done:
	s_ashr_i32 s7, s6, 31
	s_lshl_b64 s[6:7], s[6:7], 10
	v_lshl_add_u64 v[118:119], v[80:81], 0, s[6:7]
	s_lshl_b32 s8, s41, 4
	s_mov_b32 s9, s31
	v_mov_b32_e32 v126, v144
	v_mov_b32_e32 v127, v145
	v_mov_b32_e32 v124, v146
	v_mov_b32_e32 v125, v147
	v_mov_b32_e32 v122, v148
	v_mov_b32_e32 v123, v149
	v_mov_b32_e32 v120, v150
	v_mov_b32_e32 v121, v151
	ds_read_b128 v[40:43], v154 offset:1536
	ds_read_b128 v[44:47], v154 offset:1552
	ds_read_b128 v[64:67], v154 offset:2304
	ds_read_b128 v[68:71], v154 offset:2320
	ds_read_b128 v[56:59], v154 offset:2048
	ds_read_b128 v[60:63], v154 offset:2064
	ds_read_b128 v[72:75], v154 offset:2560
	ds_read_b128 v[76:79], v154 offset:2576
	ds_read_b32 v128, v153 offset:2816
	s_waitcnt lgkmcnt(9)
	v_pk_mul_f32 v[156:157], v[24:25], v[126:127]
	v_pk_fma_f32 v[126:127], v[116:117], v[16:17], v[126:127] op_sel_hi:[0,1,1]
	v_pk_fma_f32 v[156:157], v[124:125], v[26:27], v[156:157]
	v_pk_fma_f32 v[124:125], v[116:117], v[18:19], v[124:125] op_sel_hi:[0,1,1]
	v_pk_fma_f32 v[156:157], v[122:123], v[28:29], v[156:157]
	v_pk_fma_f32 v[122:123], v[116:117], v[20:21], v[122:123] op_sel_hi:[0,1,1]
	v_pk_fma_f32 v[156:157], v[120:121], v[30:31], v[156:157]
	v_pk_fma_f32 v[120:121], v[116:117], v[22:23], v[120:121] op_sel_hi:[0,1,1]
	v_add_f32_e32 v155, v156, v157
	s_nop 1
	v_add_f32_dpp v155, v155, v155 quad_perm:[1,0,3,2] row_mask:0xf bank_mask:0xf bound_ctrl:1
	s_nop 1
	v_add_f32_dpp v155, v155, v155 quad_perm:[2,3,0,1] row_mask:0xf bank_mask:0xf bound_ctrl:1
	s_nop 1
	v_add_f32_dpp v156, v155, v155 row_half_mirror row_mask:0xf bank_mask:0xf bound_ctrl:1
	v_pk_fma_f32 v[126:127], v[156:157], v[32:33], v[126:127] op_sel_hi:[0,1,1]
	v_pk_fma_f32 v[124:125], v[156:157], v[34:35], v[124:125] op_sel_hi:[0,1,1]
	v_pk_fma_f32 v[122:123], v[156:157], v[36:37], v[122:123] op_sel_hi:[0,1,1]
	v_pk_fma_f32 v[120:121], v[156:157], v[38:39], v[120:121] op_sel_hi:[0,1,1]
	ds_read_b128 v[24:27], v154 offset:3840
	ds_read_b128 v[28:31], v154 offset:3856
	ds_read_b128 v[16:19], v154 offset:3584
	ds_read_b128 v[20:23], v154 offset:3600
	ds_read_b128 v[32:35], v154 offset:4096
	ds_read_b128 v[36:39], v154 offset:4112
	ds_read_b32 v116, v153 offset:4352
	s_waitcnt lgkmcnt(7)
	v_pk_mul_f32 v[158:159], v[0:1], v[126:127]
	v_pk_mul_f32 v[156:157], v[64:65], v[126:127]
	v_pk_fma_f32 v[158:159], v[124:125], v[2:3], v[158:159]
	v_pk_fma_f32 v[156:157], v[124:125], v[66:67], v[156:157]
	v_pk_fma_f32 v[126:127], v[128:129], v[56:57], v[126:127] op_sel_hi:[0,1,1]
	v_pk_fma_f32 v[158:159], v[122:123], v[4:5], v[158:159]
	v_pk_fma_f32 v[156:157], v[122:123], v[68:69], v[156:157]
	v_pk_fma_f32 v[124:125], v[128:129], v[58:59], v[124:125] op_sel_hi:[0,1,1]
	v_pk_fma_f32 v[158:159], v[120:121], v[6:7], v[158:159]
	v_pk_fma_f32 v[156:157], v[120:121], v[70:71], v[156:157]
	ds_read_b128 v[0:3], v154 offset:3072
	ds_read_b128 v[4:7], v154 offset:3088
	v_add_f32_e32 v155, v156, v157
	v_add_f32_e32 v158, v158, v159
	ds_write_b32 v137, v158 offset:0
	v_add_f32_dpp v155, v155, v155 quad_perm:[1,0,3,2] row_mask:0xf bank_mask:0xf bound_ctrl:1
	v_pk_fma_f32 v[122:123], v[128:129], v[60:61], v[122:123] op_sel_hi:[0,1,1]
	v_pk_fma_f32 v[120:121], v[128:129], v[62:63], v[120:121] op_sel_hi:[0,1,1]
	v_add_f32_dpp v155, v155, v155 quad_perm:[2,3,0,1] row_mask:0xf bank_mask:0xf bound_ctrl:1
	s_nop 1
	v_add_f32_dpp v156, v155, v155 row_half_mirror row_mask:0xf bank_mask:0xf bound_ctrl:1
	v_pk_fma_f32 v[126:127], v[156:157], v[72:73], v[126:127] op_sel_hi:[0,1,1]
	v_pk_fma_f32 v[124:125], v[156:157], v[74:75], v[124:125] op_sel_hi:[0,1,1]
	v_pk_fma_f32 v[122:123], v[156:157], v[76:77], v[122:123] op_sel_hi:[0,1,1]
	v_pk_fma_f32 v[120:121], v[156:157], v[78:79], v[120:121] op_sel_hi:[0,1,1]
	ds_read_b128 v[64:67], v154 offset:5376
	ds_read_b128 v[68:71], v154 offset:5392
	ds_read_b128 v[56:59], v154 offset:5120
	ds_read_b128 v[60:63], v154 offset:5136
	ds_read_b128 v[72:75], v154 offset:5632
	ds_read_b128 v[76:79], v154 offset:5648
	ds_read_b32 v128, v153 offset:5888
	s_waitcnt lgkmcnt(7)
	v_pk_mul_f32 v[158:159], v[40:41], v[126:127]
	v_pk_mul_f32 v[156:157], v[24:25], v[126:127]
	v_pk_fma_f32 v[158:159], v[124:125], v[42:43], v[158:159]
	v_pk_fma_f32 v[156:157], v[124:125], v[26:27], v[156:157]
	v_pk_fma_f32 v[126:127], v[116:117], v[16:17], v[126:127] op_sel_hi:[0,1,1]
	v_pk_fma_f32 v[158:159], v[122:123], v[44:45], v[158:159]
	v_pk_fma_f32 v[156:157], v[122:123], v[28:29], v[156:157]
	v_pk_fma_f32 v[124:125], v[116:117], v[18:19], v[124:125] op_sel_hi:[0,1,1]
	v_pk_fma_f32 v[158:159], v[120:121], v[46:47], v[158:159]
	v_pk_fma_f32 v[156:157], v[120:121], v[30:31], v[156:157]
	ds_read_b128 v[40:43], v154 offset:4608
	ds_read_b128 v[44:47], v154 offset:4624
	v_add_f32_e32 v155, v156, v157
	v_add_f32_e32 v158, v158, v159
	ds_write_b32 v137, v158 offset:272
	v_add_f32_dpp v155, v155, v155 quad_perm:[1,0,3,2] row_mask:0xf bank_mask:0xf bound_ctrl:1
	v_pk_fma_f32 v[122:123], v[116:117], v[20:21], v[122:123] op_sel_hi:[0,1,1]
	v_pk_fma_f32 v[120:121], v[116:117], v[22:23], v[120:121] op_sel_hi:[0,1,1]
	v_add_f32_dpp v155, v155, v155 quad_perm:[2,3,0,1] row_mask:0xf bank_mask:0xf bound_ctrl:1
	s_nop 1
	v_add_f32_dpp v156, v155, v155 row_half_mirror row_mask:0xf bank_mask:0xf bound_ctrl:1
	v_pk_fma_f32 v[126:127], v[156:157], v[32:33], v[126:127] op_sel_hi:[0,1,1]
	v_pk_fma_f32 v[124:125], v[156:157], v[34:35], v[124:125] op_sel_hi:[0,1,1]
	v_pk_fma_f32 v[122:123], v[156:157], v[36:37], v[122:123] op_sel_hi:[0,1,1]
	v_pk_fma_f32 v[120:121], v[156:157], v[38:39], v[120:121] op_sel_hi:[0,1,1]
	ds_read_b128 v[24:27], v154 offset:6912
	ds_read_b128 v[28:31], v154 offset:6928
	ds_read_b128 v[16:19], v154 offset:6656
	ds_read_b128 v[20:23], v154 offset:6672
	ds_read_b128 v[32:35], v154 offset:7168
	ds_read_b128 v[36:39], v154 offset:7184
	ds_read_b32 v116, v153 offset:7424
	s_waitcnt lgkmcnt(7)
	v_pk_mul_f32 v[158:159], v[0:1], v[126:127]
	v_pk_mul_f32 v[156:157], v[64:65], v[126:127]
	v_pk_fma_f32 v[158:159], v[124:125], v[2:3], v[158:159]
	v_pk_fma_f32 v[156:157], v[124:125], v[66:67], v[156:157]
	v_pk_fma_f32 v[126:127], v[128:129], v[56:57], v[126:127] op_sel_hi:[0,1,1]
	v_pk_fma_f32 v[158:159], v[122:123], v[4:5], v[158:159]
	v_pk_fma_f32 v[156:157], v[122:123], v[68:69], v[156:157]
	v_pk_fma_f32 v[124:125], v[128:129], v[58:59], v[124:125] op_sel_hi:[0,1,1]
	v_pk_fma_f32 v[158:159], v[120:121], v[6:7], v[158:159]
	v_pk_fma_f32 v[156:157], v[120:121], v[70:71], v[156:157]
	ds_read_b128 v[0:3], v154 offset:6144
	ds_read_b128 v[4:7], v154 offset:6160
	v_add_f32_e32 v155, v156, v157
	v_add_f32_e32 v158, v158, v159
	ds_write_b32 v137, v158 offset:544
	v_add_f32_dpp v155, v155, v155 quad_perm:[1,0,3,2] row_mask:0xf bank_mask:0xf bound_ctrl:1
	v_pk_fma_f32 v[122:123], v[128:129], v[60:61], v[122:123] op_sel_hi:[0,1,1]
	v_pk_fma_f32 v[120:121], v[128:129], v[62:63], v[120:121] op_sel_hi:[0,1,1]
	v_add_f32_dpp v155, v155, v155 quad_perm:[2,3,0,1] row_mask:0xf bank_mask:0xf bound_ctrl:1
	s_nop 1
	v_add_f32_dpp v156, v155, v155 row_half_mirror row_mask:0xf bank_mask:0xf bound_ctrl:1
	v_pk_fma_f32 v[126:127], v[156:157], v[72:73], v[126:127] op_sel_hi:[0,1,1]
	v_pk_fma_f32 v[124:125], v[156:157], v[74:75], v[124:125] op_sel_hi:[0,1,1]
	v_pk_fma_f32 v[122:123], v[156:157], v[76:77], v[122:123] op_sel_hi:[0,1,1]
	v_pk_fma_f32 v[120:121], v[156:157], v[78:79], v[120:121] op_sel_hi:[0,1,1]
	ds_read_b128 v[64:67], v154 offset:8448
	ds_read_b128 v[68:71], v154 offset:8464
	ds_read_b128 v[56:59], v154 offset:8192
	ds_read_b128 v[60:63], v154 offset:8208
	ds_read_b128 v[72:75], v154 offset:8704
	ds_read_b128 v[76:79], v154 offset:8720
	ds_read_b32 v128, v153 offset:8960
	s_waitcnt lgkmcnt(7)
	v_pk_mul_f32 v[158:159], v[40:41], v[126:127]
	v_pk_mul_f32 v[156:157], v[24:25], v[126:127]
	v_pk_fma_f32 v[158:159], v[124:125], v[42:43], v[158:159]
	v_pk_fma_f32 v[156:157], v[124:125], v[26:27], v[156:157]
	v_pk_fma_f32 v[126:127], v[116:117], v[16:17], v[126:127] op_sel_hi:[0,1,1]
	v_pk_fma_f32 v[158:159], v[122:123], v[44:45], v[158:159]
	v_pk_fma_f32 v[156:157], v[122:123], v[28:29], v[156:157]
	v_pk_fma_f32 v[124:125], v[116:117], v[18:19], v[124:125] op_sel_hi:[0,1,1]
	v_pk_fma_f32 v[158:159], v[120:121], v[46:47], v[158:159]
	v_pk_fma_f32 v[156:157], v[120:121], v[30:31], v[156:157]
	ds_read_b128 v[40:43], v154 offset:7680
	ds_read_b128 v[44:47], v154 offset:7696
	v_add_f32_e32 v155, v156, v157
	v_add_f32_e32 v158, v158, v159
	ds_write_b32 v137, v158 offset:816
	v_add_f32_dpp v155, v155, v155 quad_perm:[1,0,3,2] row_mask:0xf bank_mask:0xf bound_ctrl:1
	v_pk_fma_f32 v[122:123], v[116:117], v[20:21], v[122:123] op_sel_hi:[0,1,1]
	v_pk_fma_f32 v[120:121], v[116:117], v[22:23], v[120:121] op_sel_hi:[0,1,1]
	v_add_f32_dpp v155, v155, v155 quad_perm:[2,3,0,1] row_mask:0xf bank_mask:0xf bound_ctrl:1
	s_nop 1
	v_add_f32_dpp v156, v155, v155 row_half_mirror row_mask:0xf bank_mask:0xf bound_ctrl:1
	v_pk_fma_f32 v[126:127], v[156:157], v[32:33], v[126:127] op_sel_hi:[0,1,1]
	v_pk_fma_f32 v[124:125], v[156:157], v[34:35], v[124:125] op_sel_hi:[0,1,1]
	v_pk_fma_f32 v[122:123], v[156:157], v[36:37], v[122:123] op_sel_hi:[0,1,1]
	v_pk_fma_f32 v[120:121], v[156:157], v[38:39], v[120:121] op_sel_hi:[0,1,1]
	ds_read_b128 v[24:27], v154 offset:9984
	ds_read_b128 v[28:31], v154 offset:10000
	ds_read_b128 v[16:19], v154 offset:9728
	ds_read_b128 v[20:23], v154 offset:9744
	ds_read_b128 v[32:35], v154 offset:10240
	ds_read_b128 v[36:39], v154 offset:10256
	ds_read_b32 v116, v153 offset:10496
	s_waitcnt lgkmcnt(7)
	v_pk_mul_f32 v[158:159], v[0:1], v[126:127]
	v_pk_mul_f32 v[156:157], v[64:65], v[126:127]
	v_pk_fma_f32 v[158:159], v[124:125], v[2:3], v[158:159]
	v_pk_fma_f32 v[156:157], v[124:125], v[66:67], v[156:157]
	v_pk_fma_f32 v[126:127], v[128:129], v[56:57], v[126:127] op_sel_hi:[0,1,1]
	v_pk_fma_f32 v[158:159], v[122:123], v[4:5], v[158:159]
	v_pk_fma_f32 v[156:157], v[122:123], v[68:69], v[156:157]
	v_pk_fma_f32 v[124:125], v[128:129], v[58:59], v[124:125] op_sel_hi:[0,1,1]
	v_pk_fma_f32 v[158:159], v[120:121], v[6:7], v[158:159]
	v_pk_fma_f32 v[156:157], v[120:121], v[70:71], v[156:157]
	ds_read_b128 v[0:3], v154 offset:9216
	ds_read_b128 v[4:7], v154 offset:9232
	v_add_f32_e32 v155, v156, v157
	v_add_f32_e32 v158, v158, v159
	ds_write_b32 v137, v158 offset:1088
	v_add_f32_dpp v155, v155, v155 quad_perm:[1,0,3,2] row_mask:0xf bank_mask:0xf bound_ctrl:1
	v_pk_fma_f32 v[122:123], v[128:129], v[60:61], v[122:123] op_sel_hi:[0,1,1]
	v_pk_fma_f32 v[120:121], v[128:129], v[62:63], v[120:121] op_sel_hi:[0,1,1]
	v_add_f32_dpp v155, v155, v155 quad_perm:[2,3,0,1] row_mask:0xf bank_mask:0xf bound_ctrl:1
	s_nop 1
	v_add_f32_dpp v156, v155, v155 row_half_mirror row_mask:0xf bank_mask:0xf bound_ctrl:1
	v_pk_fma_f32 v[126:127], v[156:157], v[72:73], v[126:127] op_sel_hi:[0,1,1]
	v_pk_fma_f32 v[124:125], v[156:157], v[74:75], v[124:125] op_sel_hi:[0,1,1]
	v_pk_fma_f32 v[122:123], v[156:157], v[76:77], v[122:123] op_sel_hi:[0,1,1]
	v_pk_fma_f32 v[120:121], v[156:157], v[78:79], v[120:121] op_sel_hi:[0,1,1]
	ds_read_b128 v[64:67], v154 offset:11520
	ds_read_b128 v[68:71], v154 offset:11536
	ds_read_b128 v[56:59], v154 offset:11264
	ds_read_b128 v[60:63], v154 offset:11280
	ds_read_b128 v[72:75], v154 offset:11776
	ds_read_b128 v[76:79], v154 offset:11792
	ds_read_b32 v128, v153 offset:12032
	ds_read_b128 v[48:51], v154 offset:11008
	ds_read_b128 v[52:55], v154 offset:11024
	s_waitcnt lgkmcnt(9)
; #define LAS __attribute__((address_space(3)))
; DI unsigned pack2(float lo, float hi) { f32x2 v = {lo, hi}; return __builtin_bit_cast(unsigned, __builtin_convertvector(v, bf16x2_t)); }
; DI void scan_item(PP p, int l, int item, LAS unsigned char* lds) {
;     ...
;                 if ((st & 6) == 6) {
;                     const LAS float* rp = ypl + (ks * 68 - lane) + (lane & ~7);
;                     const f32x4 q0 = *(const LAS f32x4*)rp, q1 = *(const LAS f32x4*)(rp + 4);
;                     Yl[(ptrdiff_t)(st - 6) * ystep] = (u16)(pack2(((q0[0] + q0[1]) + (q0[2] + q0[3])) + ((q1[0] + q1[1]) + (q1[2] + q1[3])), 0.f) & 0xffffu);
;                 }
	v_pk_mul_f32 v[158:159], v[40:41], v[126:127]
	v_pk_mul_f32 v[156:157], v[24:25], v[126:127]
	v_pk_fma_f32 v[158:159], v[124:125], v[42:43], v[158:159]
	v_pk_fma_f32 v[156:157], v[124:125], v[26:27], v[156:157]
	v_pk_fma_f32 v[126:127], v[116:117], v[16:17], v[126:127] op_sel_hi:[0,1,1]
	v_pk_fma_f32 v[158:159], v[122:123], v[44:45], v[158:159]
	v_pk_fma_f32 v[156:157], v[122:123], v[28:29], v[156:157]
	v_pk_fma_f32 v[124:125], v[116:117], v[18:19], v[124:125] op_sel_hi:[0,1,1]
	v_pk_fma_f32 v[158:159], v[120:121], v[46:47], v[158:159]
	v_pk_fma_f32 v[156:157], v[120:121], v[30:31], v[156:157]
	ds_read_b128 v[40:43], v154 offset:10752
	ds_read_b128 v[44:47], v154 offset:10768
	v_add_f32_e32 v155, v156, v157
	v_add_f32_e32 v158, v158, v159
	ds_write_b32 v137, v158 offset:1360
	v_add_f32_dpp v155, v155, v155 quad_perm:[1,0,3,2] row_mask:0xf bank_mask:0xf bound_ctrl:1
	v_pk_fma_f32 v[122:123], v[116:117], v[20:21], v[122:123] op_sel_hi:[0,1,1]
	v_pk_fma_f32 v[120:121], v[116:117], v[22:23], v[120:121] op_sel_hi:[0,1,1]
	v_add_f32_dpp v155, v155, v155 quad_perm:[2,3,0,1] row_mask:0xf bank_mask:0xf bound_ctrl:1
	s_nop 1
	v_add_f32_dpp v156, v155, v155 row_half_mirror row_mask:0xf bank_mask:0xf bound_ctrl:1
	v_pk_fma_f32 v[126:127], v[156:157], v[32:33], v[126:127] op_sel_hi:[0,1,1]
	v_pk_fma_f32 v[124:125], v[156:157], v[34:35], v[124:125] op_sel_hi:[0,1,1]
	v_pk_fma_f32 v[122:123], v[156:157], v[36:37], v[122:123] op_sel_hi:[0,1,1]
	v_pk_fma_f32 v[120:121], v[156:157], v[38:39], v[120:121] op_sel_hi:[0,1,1]
	ds_read_b128 v[24:27], v154 offset:13056
	ds_read_b128 v[28:31], v154 offset:13072
	ds_read_b128 v[16:19], v154 offset:12800
	ds_read_b128 v[20:23], v154 offset:12816
	ds_read_b128 v[32:35], v154 offset:13312
	ds_read_b128 v[36:39], v154 offset:13328
	ds_read_b32 v116, v153 offset:13568
	s_waitcnt lgkmcnt(7)
	v_pk_mul_f32 v[158:159], v[0:1], v[126:127]
	v_pk_mul_f32 v[156:157], v[64:65], v[126:127]
	v_pk_fma_f32 v[158:159], v[124:125], v[2:3], v[158:159]
	v_pk_fma_f32 v[156:157], v[124:125], v[66:67], v[156:157]
	v_pk_fma_f32 v[126:127], v[128:129], v[56:57], v[126:127] op_sel_hi:[0,1,1]
	v_pk_fma_f32 v[158:159], v[122:123], v[4:5], v[158:159]
	v_pk_fma_f32 v[156:157], v[122:123], v[68:69], v[156:157]
	v_pk_fma_f32 v[124:125], v[128:129], v[58:59], v[124:125] op_sel_hi:[0,1,1]
	v_pk_fma_f32 v[158:159], v[120:121], v[6:7], v[158:159]
	v_pk_fma_f32 v[156:157], v[120:121], v[70:71], v[156:157]
	ds_read_b128 v[0:3], v154 offset:12288
	ds_read_b128 v[4:7], v154 offset:12304
	v_add_f32_e32 v155, v156, v157
	v_add_f32_e32 v158, v158, v159
	ds_write_b32 v137, v158 offset:1632
	v_add_f32_dpp v155, v155, v155 quad_perm:[1,0,3,2] row_mask:0xf bank_mask:0xf bound_ctrl:1
	v_pk_fma_f32 v[122:123], v[128:129], v[60:61], v[122:123] op_sel_hi:[0,1,1]
	v_pk_fma_f32 v[120:121], v[128:129], v[62:63], v[120:121] op_sel_hi:[0,1,1]
	v_add_f32_dpp v155, v155, v155 quad_perm:[2,3,0,1] row_mask:0xf bank_mask:0xf bound_ctrl:1
	s_nop 1
	v_add_f32_dpp v156, v155, v155 row_half_mirror row_mask:0xf bank_mask:0xf bound_ctrl:1
	v_pk_fma_f32 v[126:127], v[156:157], v[72:73], v[126:127] op_sel_hi:[0,1,1]
	v_pk_fma_f32 v[124:125], v[156:157], v[74:75], v[124:125] op_sel_hi:[0,1,1]
	v_pk_fma_f32 v[122:123], v[156:157], v[76:77], v[122:123] op_sel_hi:[0,1,1]
	v_pk_fma_f32 v[120:121], v[156:157], v[78:79], v[120:121] op_sel_hi:[0,1,1]
	v_pk_mul_f32 v[158:159], v[40:41], v[126:127]
	s_nop 0
	v_pk_fma_f32 v[158:159], v[124:125], v[42:43], v[158:159]
	s_nop 0
	v_pk_fma_f32 v[158:159], v[122:123], v[44:45], v[158:159]
	s_nop 0
	v_pk_fma_f32 v[158:159], v[120:121], v[46:47], v[158:159]
	s_nop 0
	v_add_f32_e32 v158, v158, v159
	ds_write_b32 v137, v158 offset:1904
	ds_read_b128 v[82:85], v139
	ds_read_b128 v[86:89], v139 offset:16
	v_pk_mul_f32 v[126:127], v[48:49], v[126:127]
	v_pk_mul_f32 v[124:125], v[50:51], v[124:125]
	v_pk_mul_f32 v[122:123], v[52:53], v[122:123]
	v_pk_mul_f32 v[120:121], v[54:55], v[120:121]
	ds_read_b128 v[40:43], v154 offset:13824
	ds_read_b128 v[44:47], v154 offset:13840
	ds_read_b128 v[64:67], v154 offset:14592
	ds_read_b128 v[68:71], v154 offset:14608
	ds_read_b128 v[56:59], v154 offset:14336
	ds_read_b128 v[60:63], v154 offset:14352
	ds_read_b128 v[72:75], v154 offset:14848
	ds_read_b128 v[76:79], v154 offset:14864
	ds_read_b32 v128, v153 offset:15104
	s_waitcnt lgkmcnt(9)
	v_pk_mul_f32 v[156:157], v[24:25], v[126:127]
	v_pk_fma_f32 v[126:127], v[116:117], v[16:17], v[126:127] op_sel_hi:[0,1,1]
	v_pk_fma_f32 v[156:157], v[124:125], v[26:27], v[156:157]
	v_pk_fma_f32 v[124:125], v[116:117], v[18:19], v[124:125] op_sel_hi:[0,1,1]
	v_pk_fma_f32 v[156:157], v[122:123], v[28:29], v[156:157]
	v_pk_fma_f32 v[122:123], v[116:117], v[20:21], v[122:123] op_sel_hi:[0,1,1]
	v_pk_fma_f32 v[156:157], v[120:121], v[30:31], v[156:157]
	v_pk_fma_f32 v[120:121], v[116:117], v[22:23], v[120:121] op_sel_hi:[0,1,1]
	v_add_f32_e32 v155, v156, v157
	s_nop 1
	v_add_f32_dpp v155, v155, v155 quad_perm:[1,0,3,2] row_mask:0xf bank_mask:0xf bound_ctrl:1
	s_nop 1
	v_add_f32_dpp v155, v155, v155 quad_perm:[2,3,0,1] row_mask:0xf bank_mask:0xf bound_ctrl:1
	s_nop 1
	v_add_f32_dpp v156, v155, v155 row_half_mirror row_mask:0xf bank_mask:0xf bound_ctrl:1
	v_pk_fma_f32 v[126:127], v[156:157], v[32:33], v[126:127] op_sel_hi:[0,1,1]
	v_pk_add_f32 v[82:83], v[82:83], v[84:85]
	v_pk_fma_f32 v[124:125], v[156:157], v[34:35], v[124:125] op_sel_hi:[0,1,1]
	v_pk_add_f32 v[86:87], v[86:87], v[88:89]
	v_pk_fma_f32 v[122:123], v[156:157], v[36:37], v[122:123] op_sel_hi:[0,1,1]
	v_pk_add_f32 v[82:83], v[82:83], v[86:87]
	v_pk_fma_f32 v[120:121], v[156:157], v[38:39], v[120:121] op_sel_hi:[0,1,1]
	v_add_f32_e32 v82, v82, v83
	v_cvt_pk_bf16_f32 v82, v82, v82
	global_store_short v[118:119], v82, off
	v_lshl_add_u64 v[118:119], s[8:9], 0, v[118:119]
	ds_read_b128 v[24:27], v154 offset:16128
	ds_read_b128 v[28:31], v154 offset:16144
	ds_read_b128 v[16:19], v154 offset:15872
	ds_read_b128 v[20:23], v154 offset:15888
	ds_read_b128 v[32:35], v154 offset:16384
	ds_read_b128 v[36:39], v154 offset:16400
	ds_read_b32 v116, v153 offset:16640
	s_waitcnt lgkmcnt(7)
	v_pk_mul_f32 v[158:159], v[0:1], v[126:127]
	v_pk_mul_f32 v[156:157], v[64:65], v[126:127]
	v_pk_fma_f32 v[158:159], v[124:125], v[2:3], v[158:159]
	v_pk_fma_f32 v[156:157], v[124:125], v[66:67], v[156:157]
	v_pk_fma_f32 v[126:127], v[128:129], v[56:57], v[126:127] op_sel_hi:[0,1,1]
	v_pk_fma_f32 v[158:159], v[122:123], v[4:5], v[158:159]
	v_pk_fma_f32 v[156:157], v[122:123], v[68:69], v[156:157]
	v_pk_fma_f32 v[124:125], v[128:129], v[58:59], v[124:125] op_sel_hi:[0,1,1]
	v_pk_fma_f32 v[158:159], v[120:121], v[6:7], v[158:159]
	v_pk_fma_f32 v[156:157], v[120:121], v[70:71], v[156:157]
	ds_read_b128 v[0:3], v154 offset:15360
	ds_read_b128 v[4:7], v154 offset:15376
	v_add_f32_e32 v155, v156, v157
	v_add_f32_e32 v158, v158, v159
	ds_write_b32 v137, v158 offset:0
	v_add_f32_dpp v155, v155, v155 quad_perm:[1,0,3,2] row_mask:0xf bank_mask:0xf bound_ctrl:1
	v_pk_fma_f32 v[122:123], v[128:129], v[60:61], v[122:123] op_sel_hi:[0,1,1]
	v_pk_fma_f32 v[120:121], v[128:129], v[62:63], v[120:121] op_sel_hi:[0,1,1]
	v_add_f32_dpp v155, v155, v155 quad_perm:[2,3,0,1] row_mask:0xf bank_mask:0xf bound_ctrl:1
	s_nop 1
	v_add_f32_dpp v156, v155, v155 row_half_mirror row_mask:0xf bank_mask:0xf bound_ctrl:1
	v_pk_fma_f32 v[126:127], v[156:157], v[72:73], v[126:127] op_sel_hi:[0,1,1]
	v_pk_fma_f32 v[124:125], v[156:157], v[74:75], v[124:125] op_sel_hi:[0,1,1]
	v_pk_fma_f32 v[122:123], v[156:157], v[76:77], v[122:123] op_sel_hi:[0,1,1]
	v_pk_fma_f32 v[120:121], v[156:157], v[78:79], v[120:121] op_sel_hi:[0,1,1]
	ds_read_b128 v[64:67], v154 offset:17664
	ds_read_b128 v[68:71], v154 offset:17680
	ds_read_b128 v[56:59], v154 offset:17408
	ds_read_b128 v[60:63], v154 offset:17424
	ds_read_b128 v[72:75], v154 offset:17920
	ds_read_b128 v[76:79], v154 offset:17936
	ds_read_b32 v128, v153 offset:18176
	s_waitcnt lgkmcnt(7)
	v_pk_mul_f32 v[158:159], v[40:41], v[126:127]
	v_pk_mul_f32 v[156:157], v[24:25], v[126:127]
	v_pk_fma_f32 v[158:159], v[124:125], v[42:43], v[158:159]
	v_pk_fma_f32 v[156:157], v[124:125], v[26:27], v[156:157]
	v_pk_fma_f32 v[126:127], v[116:117], v[16:17], v[126:127] op_sel_hi:[0,1,1]
	v_pk_fma_f32 v[158:159], v[122:123], v[44:45], v[158:159]
	v_pk_fma_f32 v[156:157], v[122:123], v[28:29], v[156:157]
	v_pk_fma_f32 v[124:125], v[116:117], v[18:19], v[124:125] op_sel_hi:[0,1,1]
	v_pk_fma_f32 v[158:159], v[120:121], v[46:47], v[158:159]
	v_pk_fma_f32 v[156:157], v[120:121], v[30:31], v[156:157]
	ds_read_b128 v[40:43], v154 offset:16896
	ds_read_b128 v[44:47], v154 offset:16912
	v_add_f32_e32 v155, v156, v157
	v_add_f32_e32 v158, v158, v159
	ds_write_b32 v137, v158 offset:272
	v_add_f32_dpp v155, v155, v155 quad_perm:[1,0,3,2] row_mask:0xf bank_mask:0xf bound_ctrl:1
	v_pk_fma_f32 v[122:123], v[116:117], v[20:21], v[122:123] op_sel_hi:[0,1,1]
	v_pk_fma_f32 v[120:121], v[116:117], v[22:23], v[120:121] op_sel_hi:[0,1,1]
	v_add_f32_dpp v155, v155, v155 quad_perm:[2,3,0,1] row_mask:0xf bank_mask:0xf bound_ctrl:1
	s_nop 1
	v_add_f32_dpp v156, v155, v155 row_half_mirror row_mask:0xf bank_mask:0xf bound_ctrl:1
	v_pk_fma_f32 v[126:127], v[156:157], v[32:33], v[126:127] op_sel_hi:[0,1,1]
	v_pk_fma_f32 v[124:125], v[156:157], v[34:35], v[124:125] op_sel_hi:[0,1,1]
	v_pk_fma_f32 v[122:123], v[156:157], v[36:37], v[122:123] op_sel_hi:[0,1,1]
	v_pk_fma_f32 v[120:121], v[156:157], v[38:39], v[120:121] op_sel_hi:[0,1,1]
	ds_read_b128 v[24:27], v154 offset:19200
	ds_read_b128 v[28:31], v154 offset:19216
	ds_read_b128 v[16:19], v154 offset:18944
	ds_read_b128 v[20:23], v154 offset:18960
	ds_read_b128 v[32:35], v154 offset:19456
	ds_read_b128 v[36:39], v154 offset:19472
	ds_read_b32 v116, v153 offset:19712
	s_waitcnt lgkmcnt(7)
	v_pk_mul_f32 v[158:159], v[0:1], v[126:127]
	v_pk_mul_f32 v[156:157], v[64:65], v[126:127]
	v_pk_fma_f32 v[158:159], v[124:125], v[2:3], v[158:159]
	v_pk_fma_f32 v[156:157], v[124:125], v[66:67], v[156:157]
	v_pk_fma_f32 v[126:127], v[128:129], v[56:57], v[126:127] op_sel_hi:[0,1,1]
	v_pk_fma_f32 v[158:159], v[122:123], v[4:5], v[158:159]
	v_pk_fma_f32 v[156:157], v[122:123], v[68:69], v[156:157]
	v_pk_fma_f32 v[124:125], v[128:129], v[58:59], v[124:125] op_sel_hi:[0,1,1]
	v_pk_fma_f32 v[158:159], v[120:121], v[6:7], v[158:159]
	v_pk_fma_f32 v[156:157], v[120:121], v[70:71], v[156:157]
	ds_read_b128 v[0:3], v154 offset:18432
	ds_read_b128 v[4:7], v154 offset:18448
	v_add_f32_e32 v155, v156, v157
	v_add_f32_e32 v158, v158, v159
	ds_write_b32 v137, v158 offset:544
	v_add_f32_dpp v155, v155, v155 quad_perm:[1,0,3,2] row_mask:0xf bank_mask:0xf bound_ctrl:1
	v_pk_fma_f32 v[122:123], v[128:129], v[60:61], v[122:123] op_sel_hi:[0,1,1]
	v_pk_fma_f32 v[120:121], v[128:129], v[62:63], v[120:121] op_sel_hi:[0,1,1]
	v_add_f32_dpp v155, v155, v155 quad_perm:[2,3,0,1] row_mask:0xf bank_mask:0xf bound_ctrl:1
	s_nop 1
	v_add_f32_dpp v156, v155, v155 row_half_mirror row_mask:0xf bank_mask:0xf bound_ctrl:1
	v_pk_fma_f32 v[126:127], v[156:157], v[72:73], v[126:127] op_sel_hi:[0,1,1]
	v_pk_fma_f32 v[124:125], v[156:157], v[74:75], v[124:125] op_sel_hi:[0,1,1]
	v_pk_fma_f32 v[122:123], v[156:157], v[76:77], v[122:123] op_sel_hi:[0,1,1]
	v_pk_fma_f32 v[120:121], v[156:157], v[78:79], v[120:121] op_sel_hi:[0,1,1]
	ds_read_b128 v[64:67], v154 offset:20736
	ds_read_b128 v[68:71], v154 offset:20752
	ds_read_b128 v[56:59], v154 offset:20480
	ds_read_b128 v[60:63], v154 offset:20496
	ds_read_b128 v[72:75], v154 offset:20992
	ds_read_b128 v[76:79], v154 offset:21008
	ds_read_b32 v128, v153 offset:21248
	s_waitcnt lgkmcnt(7)
	v_pk_mul_f32 v[158:159], v[40:41], v[126:127]
	v_pk_mul_f32 v[156:157], v[24:25], v[126:127]
	v_pk_fma_f32 v[158:159], v[124:125], v[42:43], v[158:159]
	v_pk_fma_f32 v[156:157], v[124:125], v[26:27], v[156:157]
	v_pk_fma_f32 v[126:127], v[116:117], v[16:17], v[126:127] op_sel_hi:[0,1,1]
	v_pk_fma_f32 v[158:159], v[122:123], v[44:45], v[158:159]
	v_pk_fma_f32 v[156:157], v[122:123], v[28:29], v[156:157]
	v_pk_fma_f32 v[124:125], v[116:117], v[18:19], v[124:125] op_sel_hi:[0,1,1]
	v_pk_fma_f32 v[158:159], v[120:121], v[46:47], v[158:159]
	v_pk_fma_f32 v[156:157], v[120:121], v[30:31], v[156:157]
	ds_read_b128 v[40:43], v154 offset:19968
	ds_read_b128 v[44:47], v154 offset:19984
	v_add_f32_e32 v155, v156, v157
	v_add_f32_e32 v158, v158, v159
	ds_write_b32 v137, v158 offset:816
	v_add_f32_dpp v155, v155, v155 quad_perm:[1,0,3,2] row_mask:0xf bank_mask:0xf bound_ctrl:1
	v_pk_fma_f32 v[122:123], v[116:117], v[20:21], v[122:123] op_sel_hi:[0,1,1]
	v_pk_fma_f32 v[120:121], v[116:117], v[22:23], v[120:121] op_sel_hi:[0,1,1]
	v_add_f32_dpp v155, v155, v155 quad_perm:[2,3,0,1] row_mask:0xf bank_mask:0xf bound_ctrl:1
	s_nop 1
	v_add_f32_dpp v156, v155, v155 row_half_mirror row_mask:0xf bank_mask:0xf bound_ctrl:1
	v_pk_fma_f32 v[126:127], v[156:157], v[32:33], v[126:127] op_sel_hi:[0,1,1]
	v_pk_fma_f32 v[124:125], v[156:157], v[34:35], v[124:125] op_sel_hi:[0,1,1]
	v_pk_fma_f32 v[122:123], v[156:157], v[36:37], v[122:123] op_sel_hi:[0,1,1]
	v_pk_fma_f32 v[120:121], v[156:157], v[38:39], v[120:121] op_sel_hi:[0,1,1]
	ds_read_b128 v[24:27], v154 offset:22272
	ds_read_b128 v[28:31], v154 offset:22288
	ds_read_b128 v[16:19], v154 offset:22016
	ds_read_b128 v[20:23], v154 offset:22032
	ds_read_b128 v[32:35], v154 offset:22528
	ds_read_b128 v[36:39], v154 offset:22544
	ds_read_b32 v116, v153 offset:22784
	s_waitcnt lgkmcnt(7)
	v_pk_mul_f32 v[158:159], v[0:1], v[126:127]
	v_pk_mul_f32 v[156:157], v[64:65], v[126:127]
	v_pk_fma_f32 v[158:159], v[124:125], v[2:3], v[158:159]
	v_pk_fma_f32 v[156:157], v[124:125], v[66:67], v[156:157]
	v_pk_fma_f32 v[126:127], v[128:129], v[56:57], v[126:127] op_sel_hi:[0,1,1]
	v_pk_fma_f32 v[158:159], v[122:123], v[4:5], v[158:159]
	v_pk_fma_f32 v[156:157], v[122:123], v[68:69], v[156:157]
	v_pk_fma_f32 v[124:125], v[128:129], v[58:59], v[124:125] op_sel_hi:[0,1,1]
	v_pk_fma_f32 v[158:159], v[120:121], v[6:7], v[158:159]
	v_pk_fma_f32 v[156:157], v[120:121], v[70:71], v[156:157]
	ds_read_b128 v[0:3], v154 offset:21504
	ds_read_b128 v[4:7], v154 offset:21520
	v_add_f32_e32 v155, v156, v157
	v_add_f32_e32 v158, v158, v159
	ds_write_b32 v137, v158 offset:1088
	v_add_f32_dpp v155, v155, v155 quad_perm:[1,0,3,2] row_mask:0xf bank_mask:0xf bound_ctrl:1
	v_pk_fma_f32 v[122:123], v[128:129], v[60:61], v[122:123] op_sel_hi:[0,1,1]
	v_pk_fma_f32 v[120:121], v[128:129], v[62:63], v[120:121] op_sel_hi:[0,1,1]
	v_add_f32_dpp v155, v155, v155 quad_perm:[2,3,0,1] row_mask:0xf bank_mask:0xf bound_ctrl:1
	s_nop 1
	v_add_f32_dpp v156, v155, v155 row_half_mirror row_mask:0xf bank_mask:0xf bound_ctrl:1
	v_pk_fma_f32 v[126:127], v[156:157], v[72:73], v[126:127] op_sel_hi:[0,1,1]
	v_pk_fma_f32 v[124:125], v[156:157], v[74:75], v[124:125] op_sel_hi:[0,1,1]
	v_pk_fma_f32 v[122:123], v[156:157], v[76:77], v[122:123] op_sel_hi:[0,1,1]
	v_pk_fma_f32 v[120:121], v[156:157], v[78:79], v[120:121] op_sel_hi:[0,1,1]
	ds_read_b128 v[64:67], v154 offset:23808
	ds_read_b128 v[68:71], v154 offset:23824
	ds_read_b128 v[56:59], v154 offset:23552
	ds_read_b128 v[60:63], v154 offset:23568
	ds_read_b128 v[72:75], v154 offset:24064
	ds_read_b128 v[76:79], v154 offset:24080
	ds_read_b32 v128, v153 offset:24320
	ds_read_b128 v[48:51], v154 offset:23296
	ds_read_b128 v[52:55], v154 offset:23312
	s_waitcnt lgkmcnt(9)
	v_pk_mul_f32 v[158:159], v[40:41], v[126:127]
	v_pk_mul_f32 v[156:157], v[24:25], v[126:127]
	v_pk_fma_f32 v[158:159], v[124:125], v[42:43], v[158:159]
	v_pk_fma_f32 v[156:157], v[124:125], v[26:27], v[156:157]
	v_pk_fma_f32 v[126:127], v[116:117], v[16:17], v[126:127] op_sel_hi:[0,1,1]
	v_pk_fma_f32 v[158:159], v[122:123], v[44:45], v[158:159]
	v_pk_fma_f32 v[156:157], v[122:123], v[28:29], v[156:157]
	v_pk_fma_f32 v[124:125], v[116:117], v[18:19], v[124:125] op_sel_hi:[0,1,1]
	v_pk_fma_f32 v[158:159], v[120:121], v[46:47], v[158:159]
	v_pk_fma_f32 v[156:157], v[120:121], v[30:31], v[156:157]
	ds_read_b128 v[40:43], v154 offset:23040
	ds_read_b128 v[44:47], v154 offset:23056
	v_add_f32_e32 v155, v156, v157
	v_add_f32_e32 v158, v158, v159
	ds_write_b32 v137, v158 offset:1360
	v_add_f32_dpp v155, v155, v155 quad_perm:[1,0,3,2] row_mask:0xf bank_mask:0xf bound_ctrl:1
	v_pk_fma_f32 v[122:123], v[116:117], v[20:21], v[122:123] op_sel_hi:[0,1,1]
	v_pk_fma_f32 v[120:121], v[116:117], v[22:23], v[120:121] op_sel_hi:[0,1,1]
	v_add_f32_dpp v155, v155, v155 quad_perm:[2,3,0,1] row_mask:0xf bank_mask:0xf bound_ctrl:1
	s_nop 1
	v_add_f32_dpp v156, v155, v155 row_half_mirror row_mask:0xf bank_mask:0xf bound_ctrl:1
	v_pk_fma_f32 v[126:127], v[156:157], v[32:33], v[126:127] op_sel_hi:[0,1,1]
	v_pk_fma_f32 v[124:125], v[156:157], v[34:35], v[124:125] op_sel_hi:[0,1,1]
	v_pk_fma_f32 v[122:123], v[156:157], v[36:37], v[122:123] op_sel_hi:[0,1,1]
	v_pk_fma_f32 v[120:121], v[156:157], v[38:39], v[120:121] op_sel_hi:[0,1,1]
	ds_read_b128 v[24:27], v154 offset:25344
	ds_read_b128 v[28:31], v154 offset:25360
	ds_read_b128 v[16:19], v154 offset:25088
	ds_read_b128 v[20:23], v154 offset:25104
	ds_read_b128 v[32:35], v154 offset:25600
	ds_read_b128 v[36:39], v154 offset:25616
	ds_read_b32 v116, v153 offset:25856
	s_waitcnt lgkmcnt(7)
; #define LAS __attribute__((address_space(3)))
; DI unsigned pack2(float lo, float hi) { f32x2 v = {lo, hi}; return __builtin_bit_cast(unsigned, __builtin_convertvector(v, bf16x2_t)); }
; DI void scan_item(PP p, int l, int item, LAS unsigned char* lds) {
;     ...
;                 if ((st & 6) == 6) {
;                     const LAS float* rp = ypl + (ks * 68 - lane) + (lane & ~7);
;                     const f32x4 q0 = *(const LAS f32x4*)rp, q1 = *(const LAS f32x4*)(rp + 4);
;                     Yl[(ptrdiff_t)(st - 6) * ystep] = (u16)(pack2(((q0[0] + q0[1]) + (q0[2] + q0[3])) + ((q1[0] + q1[1]) + (q1[2] + q1[3])), 0.f) & 0xffffu);
;                 }
	v_pk_mul_f32 v[158:159], v[0:1], v[126:127]
	v_pk_mul_f32 v[156:157], v[64:65], v[126:127]
	v_pk_fma_f32 v[158:159], v[124:125], v[2:3], v[158:159]
	v_pk_fma_f32 v[156:157], v[124:125], v[66:67], v[156:157]
	v_pk_fma_f32 v[126:127], v[128:129], v[56:57], v[126:127] op_sel_hi:[0,1,1]
	v_pk_fma_f32 v[158:159], v[122:123], v[4:5], v[158:159]
	v_pk_fma_f32 v[156:157], v[122:123], v[68:69], v[156:157]
	v_pk_fma_f32 v[124:125], v[128:129], v[58:59], v[124:125] op_sel_hi:[0,1,1]
	v_pk_fma_f32 v[158:159], v[120:121], v[6:7], v[158:159]
	v_pk_fma_f32 v[156:157], v[120:121], v[70:71], v[156:157]
	ds_read_b128 v[0:3], v154 offset:24576
	ds_read_b128 v[4:7], v154 offset:24592
	v_add_f32_e32 v155, v156, v157
	v_add_f32_e32 v158, v158, v159
	ds_write_b32 v137, v158 offset:1632
	v_add_f32_dpp v155, v155, v155 quad_perm:[1,0,3,2] row_mask:0xf bank_mask:0xf bound_ctrl:1
	v_pk_fma_f32 v[122:123], v[128:129], v[60:61], v[122:123] op_sel_hi:[0,1,1]
	v_pk_fma_f32 v[120:121], v[128:129], v[62:63], v[120:121] op_sel_hi:[0,1,1]
	v_add_f32_dpp v155, v155, v155 quad_perm:[2,3,0,1] row_mask:0xf bank_mask:0xf bound_ctrl:1
	s_nop 1
	v_add_f32_dpp v156, v155, v155 row_half_mirror row_mask:0xf bank_mask:0xf bound_ctrl:1
	v_pk_fma_f32 v[126:127], v[156:157], v[72:73], v[126:127] op_sel_hi:[0,1,1]
	v_pk_fma_f32 v[124:125], v[156:157], v[74:75], v[124:125] op_sel_hi:[0,1,1]
	v_pk_fma_f32 v[122:123], v[156:157], v[76:77], v[122:123] op_sel_hi:[0,1,1]
	v_pk_fma_f32 v[120:121], v[156:157], v[78:79], v[120:121] op_sel_hi:[0,1,1]
	v_pk_mul_f32 v[158:159], v[40:41], v[126:127]
	s_nop 0
	v_pk_fma_f32 v[158:159], v[124:125], v[42:43], v[158:159]
	s_nop 0
	v_pk_fma_f32 v[158:159], v[122:123], v[44:45], v[158:159]
	s_nop 0
	v_pk_fma_f32 v[158:159], v[120:121], v[46:47], v[158:159]
	s_nop 0
	v_add_f32_e32 v158, v158, v159
	ds_write_b32 v137, v158 offset:1904
	ds_read_b128 v[82:85], v139
	ds_read_b128 v[86:89], v139 offset:16
	v_pk_mul_f32 v[126:127], v[48:49], v[126:127]
	v_pk_mul_f32 v[124:125], v[50:51], v[124:125]
	v_pk_mul_f32 v[122:123], v[52:53], v[122:123]
	v_pk_mul_f32 v[120:121], v[54:55], v[120:121]
	ds_read_b128 v[40:43], v154 offset:26112
	ds_read_b128 v[44:47], v154 offset:26128
	ds_read_b128 v[64:67], v154 offset:26880
	ds_read_b128 v[68:71], v154 offset:26896
	ds_read_b128 v[56:59], v154 offset:26624
	ds_read_b128 v[60:63], v154 offset:26640
	ds_read_b128 v[72:75], v154 offset:27136
	ds_read_b128 v[76:79], v154 offset:27152
	ds_read_b32 v128, v153 offset:27392
	s_waitcnt lgkmcnt(9)
	v_pk_mul_f32 v[156:157], v[24:25], v[126:127]
	v_pk_fma_f32 v[126:127], v[116:117], v[16:17], v[126:127] op_sel_hi:[0,1,1]
	v_pk_fma_f32 v[156:157], v[124:125], v[26:27], v[156:157]
	v_pk_fma_f32 v[124:125], v[116:117], v[18:19], v[124:125] op_sel_hi:[0,1,1]
	v_pk_fma_f32 v[156:157], v[122:123], v[28:29], v[156:157]
	v_pk_fma_f32 v[122:123], v[116:117], v[20:21], v[122:123] op_sel_hi:[0,1,1]
	v_pk_fma_f32 v[156:157], v[120:121], v[30:31], v[156:157]
	v_pk_fma_f32 v[120:121], v[116:117], v[22:23], v[120:121] op_sel_hi:[0,1,1]
	v_add_f32_e32 v155, v156, v157
	s_nop 1
	v_add_f32_dpp v155, v155, v155 quad_perm:[1,0,3,2] row_mask:0xf bank_mask:0xf bound_ctrl:1
	s_nop 1
	v_add_f32_dpp v155, v155, v155 quad_perm:[2,3,0,1] row_mask:0xf bank_mask:0xf bound_ctrl:1
	s_nop 1
	v_add_f32_dpp v156, v155, v155 row_half_mirror row_mask:0xf bank_mask:0xf bound_ctrl:1
	v_pk_fma_f32 v[126:127], v[156:157], v[32:33], v[126:127] op_sel_hi:[0,1,1]
	v_pk_add_f32 v[82:83], v[82:83], v[84:85]
	v_pk_fma_f32 v[124:125], v[156:157], v[34:35], v[124:125] op_sel_hi:[0,1,1]
	v_pk_add_f32 v[86:87], v[86:87], v[88:89]
	v_pk_fma_f32 v[122:123], v[156:157], v[36:37], v[122:123] op_sel_hi:[0,1,1]
	v_pk_add_f32 v[82:83], v[82:83], v[86:87]
	v_pk_fma_f32 v[120:121], v[156:157], v[38:39], v[120:121] op_sel_hi:[0,1,1]
	v_add_f32_e32 v82, v82, v83
	v_cvt_pk_bf16_f32 v82, v82, v82
	global_store_short v[118:119], v82, off
	v_lshl_add_u64 v[118:119], s[8:9], 0, v[118:119]
	ds_read_b128 v[24:27], v154 offset:28416
	ds_read_b128 v[28:31], v154 offset:28432
	ds_read_b128 v[16:19], v154 offset:28160
	ds_read_b128 v[20:23], v154 offset:28176
	ds_read_b128 v[32:35], v154 offset:28672
	ds_read_b128 v[36:39], v154 offset:28688
	ds_read_b32 v116, v153 offset:28928
	s_waitcnt lgkmcnt(7)
	v_pk_mul_f32 v[158:159], v[0:1], v[126:127]
	v_pk_mul_f32 v[156:157], v[64:65], v[126:127]
	v_pk_fma_f32 v[158:159], v[124:125], v[2:3], v[158:159]
	v_pk_fma_f32 v[156:157], v[124:125], v[66:67], v[156:157]
	v_pk_fma_f32 v[126:127], v[128:129], v[56:57], v[126:127] op_sel_hi:[0,1,1]
	v_pk_fma_f32 v[158:159], v[122:123], v[4:5], v[158:159]
	v_pk_fma_f32 v[156:157], v[122:123], v[68:69], v[156:157]
	v_pk_fma_f32 v[124:125], v[128:129], v[58:59], v[124:125] op_sel_hi:[0,1,1]
	v_pk_fma_f32 v[158:159], v[120:121], v[6:7], v[158:159]
	v_pk_fma_f32 v[156:157], v[120:121], v[70:71], v[156:157]
	ds_read_b128 v[0:3], v154 offset:27648
	ds_read_b128 v[4:7], v154 offset:27664
	v_add_f32_e32 v155, v156, v157
	v_add_f32_e32 v158, v158, v159
	ds_write_b32 v137, v158 offset:0
	v_add_f32_dpp v155, v155, v155 quad_perm:[1,0,3,2] row_mask:0xf bank_mask:0xf bound_ctrl:1
	v_pk_fma_f32 v[122:123], v[128:129], v[60:61], v[122:123] op_sel_hi:[0,1,1]
	v_pk_fma_f32 v[120:121], v[128:129], v[62:63], v[120:121] op_sel_hi:[0,1,1]
	v_add_f32_dpp v155, v155, v155 quad_perm:[2,3,0,1] row_mask:0xf bank_mask:0xf bound_ctrl:1
	s_nop 1
	v_add_f32_dpp v156, v155, v155 row_half_mirror row_mask:0xf bank_mask:0xf bound_ctrl:1
	v_pk_fma_f32 v[126:127], v[156:157], v[72:73], v[126:127] op_sel_hi:[0,1,1]
	v_pk_fma_f32 v[124:125], v[156:157], v[74:75], v[124:125] op_sel_hi:[0,1,1]
	v_pk_fma_f32 v[122:123], v[156:157], v[76:77], v[122:123] op_sel_hi:[0,1,1]
	v_pk_fma_f32 v[120:121], v[156:157], v[78:79], v[120:121] op_sel_hi:[0,1,1]
	ds_read_b128 v[64:67], v154 offset:29952
	ds_read_b128 v[68:71], v154 offset:29968
	ds_read_b128 v[56:59], v154 offset:29696
	ds_read_b128 v[60:63], v154 offset:29712
	ds_read_b128 v[72:75], v154 offset:30208
	ds_read_b128 v[76:79], v154 offset:30224
	ds_read_b32 v128, v153 offset:30464
	s_waitcnt lgkmcnt(7)
; #define LAS __attribute__((address_space(3)))
; DI unsigned pack2(float lo, float hi) { f32x2 v = {lo, hi}; return __builtin_bit_cast(unsigned, __builtin_convertvector(v, bf16x2_t)); }
; DI void scan_item(PP p, int l, int item, LAS unsigned char* lds) {
;     ...
;     for (int c = 0; c < NCH; ++c) {
;         if (wid >= 4) { if (c + 1 < NCH) { fill(c + 1); if (c + 2 < NCH) gl(c + 2); } }
;         else {
;             const LAS float* sp = buf + ((c & 1) * T) * 384;
;             f32x4 Ar0, Ar1, Aw0, Aw1, Ak0, Ak1, Aa0, Aa1, Ab0, Ab1; float Avv;
;             f32x4 Br0, Br1, Bw0, Bw1, Bk0, Bk1, Ba0, Ba1, Bb0, Bb1; float Bvv;
;             SC_LD(A, sp);
;             const ptrdiff_t ystep = dir ? -512 : 512;
;             u16* Yl = Yp + (size_t)steprow(b, dir, c * T) * 512 + (ptrdiff_t)ks * ystep;
; #pragma nounroll
;             for (int st = 0; st < T; st += 2) {
;                 SC_LD(B, sp + (st + 1) * 384);
;                 SC_STEP(A, st);
;                 if (st + 2 < T) SC_LD(A, sp + (st + 2) * 384);
;                 SC_STEP(B, st + 1);
;                 if ((st & 6) == 6) {
;                     const LAS float* rp = ypl + (ks * 68 - lane) + (lane & ~7);
;                     const f32x4 q0 = *(const LAS f32x4*)rp, q1 = *(const LAS f32x4*)(rp + 4);
;                     Yl[(ptrdiff_t)(st - 6) * ystep] = (u16)(pack2(((q0[0] + q0[1]) + (q0[2] + q0[3])) + ((q1[0] + q1[1]) + (q1[2] + q1[3])), 0.f) & 0xffffu);
;                 }
	v_pk_mul_f32 v[158:159], v[40:41], v[126:127]
	v_pk_mul_f32 v[156:157], v[24:25], v[126:127]
	v_pk_fma_f32 v[158:159], v[124:125], v[42:43], v[158:159]
	v_pk_fma_f32 v[156:157], v[124:125], v[26:27], v[156:157]
	v_pk_fma_f32 v[126:127], v[116:117], v[16:17], v[126:127] op_sel_hi:[0,1,1]
	v_pk_fma_f32 v[158:159], v[122:123], v[44:45], v[158:159]
	v_pk_fma_f32 v[156:157], v[122:123], v[28:29], v[156:157]
	v_pk_fma_f32 v[124:125], v[116:117], v[18:19], v[124:125] op_sel_hi:[0,1,1]
	v_pk_fma_f32 v[158:159], v[120:121], v[46:47], v[158:159]
	v_pk_fma_f32 v[156:157], v[120:121], v[30:31], v[156:157]
	ds_read_b128 v[40:43], v154 offset:29184
	ds_read_b128 v[44:47], v154 offset:29200
	v_add_f32_e32 v155, v156, v157
	v_add_f32_e32 v158, v158, v159
	ds_write_b32 v137, v158 offset:272
	v_add_f32_dpp v155, v155, v155 quad_perm:[1,0,3,2] row_mask:0xf bank_mask:0xf bound_ctrl:1
	v_pk_fma_f32 v[122:123], v[116:117], v[20:21], v[122:123] op_sel_hi:[0,1,1]
	v_pk_fma_f32 v[120:121], v[116:117], v[22:23], v[120:121] op_sel_hi:[0,1,1]
	v_add_f32_dpp v155, v155, v155 quad_perm:[2,3,0,1] row_mask:0xf bank_mask:0xf bound_ctrl:1
	s_nop 1
	v_add_f32_dpp v156, v155, v155 row_half_mirror row_mask:0xf bank_mask:0xf bound_ctrl:1
	v_pk_fma_f32 v[126:127], v[156:157], v[32:33], v[126:127] op_sel_hi:[0,1,1]
	v_pk_fma_f32 v[124:125], v[156:157], v[34:35], v[124:125] op_sel_hi:[0,1,1]
	v_pk_fma_f32 v[122:123], v[156:157], v[36:37], v[122:123] op_sel_hi:[0,1,1]
	v_pk_fma_f32 v[120:121], v[156:157], v[38:39], v[120:121] op_sel_hi:[0,1,1]
	ds_read_b128 v[24:27], v154 offset:31488
	ds_read_b128 v[28:31], v154 offset:31504
	ds_read_b128 v[16:19], v154 offset:31232
	ds_read_b128 v[20:23], v154 offset:31248
	ds_read_b128 v[32:35], v154 offset:31744
	ds_read_b128 v[36:39], v154 offset:31760
	ds_read_b32 v116, v153 offset:32000
	s_waitcnt lgkmcnt(7)
	v_pk_mul_f32 v[158:159], v[0:1], v[126:127]
	v_pk_mul_f32 v[156:157], v[64:65], v[126:127]
	v_pk_fma_f32 v[158:159], v[124:125], v[2:3], v[158:159]
	v_pk_fma_f32 v[156:157], v[124:125], v[66:67], v[156:157]
	v_pk_fma_f32 v[126:127], v[128:129], v[56:57], v[126:127] op_sel_hi:[0,1,1]
	v_pk_fma_f32 v[158:159], v[122:123], v[4:5], v[158:159]
	v_pk_fma_f32 v[156:157], v[122:123], v[68:69], v[156:157]
	v_pk_fma_f32 v[124:125], v[128:129], v[58:59], v[124:125] op_sel_hi:[0,1,1]
	v_pk_fma_f32 v[158:159], v[120:121], v[6:7], v[158:159]
	v_pk_fma_f32 v[156:157], v[120:121], v[70:71], v[156:157]
	ds_read_b128 v[0:3], v154 offset:30720
	ds_read_b128 v[4:7], v154 offset:30736
	v_add_f32_e32 v155, v156, v157
	v_add_f32_e32 v158, v158, v159
	ds_write_b32 v137, v158 offset:544
	v_add_f32_dpp v155, v155, v155 quad_perm:[1,0,3,2] row_mask:0xf bank_mask:0xf bound_ctrl:1
	v_pk_fma_f32 v[122:123], v[128:129], v[60:61], v[122:123] op_sel_hi:[0,1,1]
	v_pk_fma_f32 v[120:121], v[128:129], v[62:63], v[120:121] op_sel_hi:[0,1,1]
	v_add_f32_dpp v155, v155, v155 quad_perm:[2,3,0,1] row_mask:0xf bank_mask:0xf bound_ctrl:1
	s_nop 1
	v_add_f32_dpp v156, v155, v155 row_half_mirror row_mask:0xf bank_mask:0xf bound_ctrl:1
	v_pk_fma_f32 v[126:127], v[156:157], v[72:73], v[126:127] op_sel_hi:[0,1,1]
	v_pk_fma_f32 v[124:125], v[156:157], v[74:75], v[124:125] op_sel_hi:[0,1,1]
	v_pk_fma_f32 v[122:123], v[156:157], v[76:77], v[122:123] op_sel_hi:[0,1,1]
	v_pk_fma_f32 v[120:121], v[156:157], v[78:79], v[120:121] op_sel_hi:[0,1,1]
	ds_read_b128 v[64:67], v154 offset:33024
	ds_read_b128 v[68:71], v154 offset:33040
	ds_read_b128 v[56:59], v154 offset:32768
	ds_read_b128 v[60:63], v154 offset:32784
	ds_read_b128 v[72:75], v154 offset:33280
	ds_read_b128 v[76:79], v154 offset:33296
	ds_read_b32 v128, v153 offset:33536
	s_waitcnt lgkmcnt(7)
	v_pk_mul_f32 v[158:159], v[40:41], v[126:127]
	v_pk_mul_f32 v[156:157], v[24:25], v[126:127]
	v_pk_fma_f32 v[158:159], v[124:125], v[42:43], v[158:159]
	v_pk_fma_f32 v[156:157], v[124:125], v[26:27], v[156:157]
	v_pk_fma_f32 v[126:127], v[116:117], v[16:17], v[126:127] op_sel_hi:[0,1,1]
	v_pk_fma_f32 v[158:159], v[122:123], v[44:45], v[158:159]
	v_pk_fma_f32 v[156:157], v[122:123], v[28:29], v[156:157]
	v_pk_fma_f32 v[124:125], v[116:117], v[18:19], v[124:125] op_sel_hi:[0,1,1]
	v_pk_fma_f32 v[158:159], v[120:121], v[46:47], v[158:159]
	v_pk_fma_f32 v[156:157], v[120:121], v[30:31], v[156:157]
	ds_read_b128 v[40:43], v154 offset:32256
	ds_read_b128 v[44:47], v154 offset:32272
	v_add_f32_e32 v155, v156, v157
	v_add_f32_e32 v158, v158, v159
	ds_write_b32 v137, v158 offset:816
	v_add_f32_dpp v155, v155, v155 quad_perm:[1,0,3,2] row_mask:0xf bank_mask:0xf bound_ctrl:1
	v_pk_fma_f32 v[122:123], v[116:117], v[20:21], v[122:123] op_sel_hi:[0,1,1]
	v_pk_fma_f32 v[120:121], v[116:117], v[22:23], v[120:121] op_sel_hi:[0,1,1]
	v_add_f32_dpp v155, v155, v155 quad_perm:[2,3,0,1] row_mask:0xf bank_mask:0xf bound_ctrl:1
	s_nop 1
	v_add_f32_dpp v156, v155, v155 row_half_mirror row_mask:0xf bank_mask:0xf bound_ctrl:1
	v_pk_fma_f32 v[126:127], v[156:157], v[32:33], v[126:127] op_sel_hi:[0,1,1]
	v_pk_fma_f32 v[124:125], v[156:157], v[34:35], v[124:125] op_sel_hi:[0,1,1]
	v_pk_fma_f32 v[122:123], v[156:157], v[36:37], v[122:123] op_sel_hi:[0,1,1]
	v_pk_fma_f32 v[120:121], v[156:157], v[38:39], v[120:121] op_sel_hi:[0,1,1]
	ds_read_b128 v[24:27], v154 offset:34560
	ds_read_b128 v[28:31], v154 offset:34576
	ds_read_b128 v[16:19], v154 offset:34304
	ds_read_b128 v[20:23], v154 offset:34320
	ds_read_b128 v[32:35], v154 offset:34816
	ds_read_b128 v[36:39], v154 offset:34832
	ds_read_b32 v116, v153 offset:35072
	s_waitcnt lgkmcnt(7)
; #define LAS __attribute__((address_space(3)))
; DI unsigned pack2(float lo, float hi) { f32x2 v = {lo, hi}; return __builtin_bit_cast(unsigned, __builtin_convertvector(v, bf16x2_t)); }
; DI void scan_item(PP p, int l, int item, LAS unsigned char* lds) {
;     ...
;     for (int c = 0; c < NCH; ++c) {
;         if (wid >= 4) { if (c + 1 < NCH) { fill(c + 1); if (c + 2 < NCH) gl(c + 2); } }
;         else {
;             const LAS float* sp = buf + ((c & 1) * T) * 384;
;             f32x4 Ar0, Ar1, Aw0, Aw1, Ak0, Ak1, Aa0, Aa1, Ab0, Ab1; float Avv;
;             f32x4 Br0, Br1, Bw0, Bw1, Bk0, Bk1, Ba0, Ba1, Bb0, Bb1; float Bvv;
;             SC_LD(A, sp);
;             const ptrdiff_t ystep = dir ? -512 : 512;
;             u16* Yl = Yp + (size_t)steprow(b, dir, c * T) * 512 + (ptrdiff_t)ks * ystep;
; #pragma nounroll
;             for (int st = 0; st < T; st += 2) {
;                 SC_LD(B, sp + (st + 1) * 384);
;                 SC_STEP(A, st);
;                 if (st + 2 < T) SC_LD(A, sp + (st + 2) * 384);
;                 SC_STEP(B, st + 1);
;                 if ((st & 6) == 6) {
;                     const LAS float* rp = ypl + (ks * 68 - lane) + (lane & ~7);
;                     const f32x4 q0 = *(const LAS f32x4*)rp, q1 = *(const LAS f32x4*)(rp + 4);
;                     Yl[(ptrdiff_t)(st - 6) * ystep] = (u16)(pack2(((q0[0] + q0[1]) + (q0[2] + q0[3])) + ((q1[0] + q1[1]) + (q1[2] + q1[3])), 0.f) & 0xffffu);
;                 }
	v_pk_mul_f32 v[158:159], v[0:1], v[126:127]
	v_pk_mul_f32 v[156:157], v[64:65], v[126:127]
	v_pk_fma_f32 v[158:159], v[124:125], v[2:3], v[158:159]
	v_pk_fma_f32 v[156:157], v[124:125], v[66:67], v[156:157]
	v_pk_fma_f32 v[126:127], v[128:129], v[56:57], v[126:127] op_sel_hi:[0,1,1]
	v_pk_fma_f32 v[158:159], v[122:123], v[4:5], v[158:159]
	v_pk_fma_f32 v[156:157], v[122:123], v[68:69], v[156:157]
	v_pk_fma_f32 v[124:125], v[128:129], v[58:59], v[124:125] op_sel_hi:[0,1,1]
	v_pk_fma_f32 v[158:159], v[120:121], v[6:7], v[158:159]
	v_pk_fma_f32 v[156:157], v[120:121], v[70:71], v[156:157]
	ds_read_b128 v[0:3], v154 offset:33792
	ds_read_b128 v[4:7], v154 offset:33808
	v_add_f32_e32 v155, v156, v157
	v_add_f32_e32 v158, v158, v159
	ds_write_b32 v137, v158 offset:1088
	v_add_f32_dpp v155, v155, v155 quad_perm:[1,0,3,2] row_mask:0xf bank_mask:0xf bound_ctrl:1
	v_pk_fma_f32 v[122:123], v[128:129], v[60:61], v[122:123] op_sel_hi:[0,1,1]
	v_pk_fma_f32 v[120:121], v[128:129], v[62:63], v[120:121] op_sel_hi:[0,1,1]
	v_add_f32_dpp v155, v155, v155 quad_perm:[2,3,0,1] row_mask:0xf bank_mask:0xf bound_ctrl:1
	s_nop 1
	v_add_f32_dpp v156, v155, v155 row_half_mirror row_mask:0xf bank_mask:0xf bound_ctrl:1
	v_pk_fma_f32 v[126:127], v[156:157], v[72:73], v[126:127] op_sel_hi:[0,1,1]
	v_pk_fma_f32 v[124:125], v[156:157], v[74:75], v[124:125] op_sel_hi:[0,1,1]
	v_pk_fma_f32 v[122:123], v[156:157], v[76:77], v[122:123] op_sel_hi:[0,1,1]
	v_pk_fma_f32 v[120:121], v[156:157], v[78:79], v[120:121] op_sel_hi:[0,1,1]
	ds_read_b128 v[64:67], v154 offset:36096
	ds_read_b128 v[68:71], v154 offset:36112
	ds_read_b128 v[56:59], v154 offset:35840
	ds_read_b128 v[60:63], v154 offset:35856
	ds_read_b128 v[72:75], v154 offset:36352
	ds_read_b128 v[76:79], v154 offset:36368
	ds_read_b32 v128, v153 offset:36608
	ds_read_b128 v[48:51], v154 offset:35584
	ds_read_b128 v[52:55], v154 offset:35600
	s_waitcnt lgkmcnt(9)
	v_pk_mul_f32 v[158:159], v[40:41], v[126:127]
	v_pk_mul_f32 v[156:157], v[24:25], v[126:127]
	v_pk_fma_f32 v[158:159], v[124:125], v[42:43], v[158:159]
	v_pk_fma_f32 v[156:157], v[124:125], v[26:27], v[156:157]
	v_pk_fma_f32 v[126:127], v[116:117], v[16:17], v[126:127] op_sel_hi:[0,1,1]
	v_pk_fma_f32 v[158:159], v[122:123], v[44:45], v[158:159]
	v_pk_fma_f32 v[156:157], v[122:123], v[28:29], v[156:157]
	v_pk_fma_f32 v[124:125], v[116:117], v[18:19], v[124:125] op_sel_hi:[0,1,1]
	v_pk_fma_f32 v[158:159], v[120:121], v[46:47], v[158:159]
	v_pk_fma_f32 v[156:157], v[120:121], v[30:31], v[156:157]
	ds_read_b128 v[40:43], v154 offset:35328
	ds_read_b128 v[44:47], v154 offset:35344
	v_add_f32_e32 v155, v156, v157
	v_add_f32_e32 v158, v158, v159
	ds_write_b32 v137, v158 offset:1360
	v_add_f32_dpp v155, v155, v155 quad_perm:[1,0,3,2] row_mask:0xf bank_mask:0xf bound_ctrl:1
	v_pk_fma_f32 v[122:123], v[116:117], v[20:21], v[122:123] op_sel_hi:[0,1,1]
	v_pk_fma_f32 v[120:121], v[116:117], v[22:23], v[120:121] op_sel_hi:[0,1,1]
	v_add_f32_dpp v155, v155, v155 quad_perm:[2,3,0,1] row_mask:0xf bank_mask:0xf bound_ctrl:1
	s_nop 1
	v_add_f32_dpp v156, v155, v155 row_half_mirror row_mask:0xf bank_mask:0xf bound_ctrl:1
	v_pk_fma_f32 v[126:127], v[156:157], v[32:33], v[126:127] op_sel_hi:[0,1,1]
	v_pk_fma_f32 v[124:125], v[156:157], v[34:35], v[124:125] op_sel_hi:[0,1,1]
	v_pk_fma_f32 v[122:123], v[156:157], v[36:37], v[122:123] op_sel_hi:[0,1,1]
	v_pk_fma_f32 v[120:121], v[156:157], v[38:39], v[120:121] op_sel_hi:[0,1,1]
	ds_read_b128 v[24:27], v154 offset:37632
	ds_read_b128 v[28:31], v154 offset:37648
	ds_read_b128 v[16:19], v154 offset:37376
	ds_read_b128 v[20:23], v154 offset:37392
	ds_read_b128 v[32:35], v154 offset:37888
	ds_read_b128 v[36:39], v154 offset:37904
	ds_read_b32 v116, v153 offset:38144
	s_waitcnt lgkmcnt(7)
	v_pk_mul_f32 v[158:159], v[0:1], v[126:127]
	v_pk_mul_f32 v[156:157], v[64:65], v[126:127]
	v_pk_fma_f32 v[158:159], v[124:125], v[2:3], v[158:159]
	v_pk_fma_f32 v[156:157], v[124:125], v[66:67], v[156:157]
	v_pk_fma_f32 v[126:127], v[128:129], v[56:57], v[126:127] op_sel_hi:[0,1,1]
	v_pk_fma_f32 v[158:159], v[122:123], v[4:5], v[158:159]
	v_pk_fma_f32 v[156:157], v[122:123], v[68:69], v[156:157]
	v_pk_fma_f32 v[124:125], v[128:129], v[58:59], v[124:125] op_sel_hi:[0,1,1]
	v_pk_fma_f32 v[158:159], v[120:121], v[6:7], v[158:159]
	v_pk_fma_f32 v[156:157], v[120:121], v[70:71], v[156:157]
	ds_read_b128 v[0:3], v154 offset:36864
	ds_read_b128 v[4:7], v154 offset:36880
	v_add_f32_e32 v155, v156, v157
	v_add_f32_e32 v158, v158, v159
	ds_write_b32 v137, v158 offset:1632
	v_add_f32_dpp v155, v155, v155 quad_perm:[1,0,3,2] row_mask:0xf bank_mask:0xf bound_ctrl:1
	v_pk_fma_f32 v[122:123], v[128:129], v[60:61], v[122:123] op_sel_hi:[0,1,1]
	v_pk_fma_f32 v[120:121], v[128:129], v[62:63], v[120:121] op_sel_hi:[0,1,1]
	v_add_f32_dpp v155, v155, v155 quad_perm:[2,3,0,1] row_mask:0xf bank_mask:0xf bound_ctrl:1
	s_nop 1
	v_add_f32_dpp v156, v155, v155 row_half_mirror row_mask:0xf bank_mask:0xf bound_ctrl:1
	v_pk_fma_f32 v[126:127], v[156:157], v[72:73], v[126:127] op_sel_hi:[0,1,1]
	v_pk_fma_f32 v[124:125], v[156:157], v[74:75], v[124:125] op_sel_hi:[0,1,1]
	v_pk_fma_f32 v[122:123], v[156:157], v[76:77], v[122:123] op_sel_hi:[0,1,1]
	v_pk_fma_f32 v[120:121], v[156:157], v[78:79], v[120:121] op_sel_hi:[0,1,1]
	v_pk_mul_f32 v[158:159], v[40:41], v[126:127]
	s_nop 0
	v_pk_fma_f32 v[158:159], v[124:125], v[42:43], v[158:159]
	s_nop 0
	v_pk_fma_f32 v[158:159], v[122:123], v[44:45], v[158:159]
	s_nop 0
	v_pk_fma_f32 v[158:159], v[120:121], v[46:47], v[158:159]
	s_nop 0
	v_add_f32_e32 v158, v158, v159
	ds_write_b32 v137, v158 offset:1904
	ds_read_b128 v[82:85], v139
	ds_read_b128 v[86:89], v139 offset:16
	v_pk_mul_f32 v[126:127], v[48:49], v[126:127]
	v_pk_mul_f32 v[124:125], v[50:51], v[124:125]
	v_pk_mul_f32 v[122:123], v[52:53], v[122:123]
	v_pk_mul_f32 v[120:121], v[54:55], v[120:121]
	ds_read_b128 v[40:43], v154 offset:38400
	ds_read_b128 v[44:47], v154 offset:38416
	ds_read_b128 v[64:67], v154 offset:39168
	ds_read_b128 v[68:71], v154 offset:39184
	ds_read_b128 v[56:59], v154 offset:38912
	ds_read_b128 v[60:63], v154 offset:38928
	ds_read_b128 v[72:75], v154 offset:39424
	ds_read_b128 v[76:79], v154 offset:39440
	ds_read_b32 v128, v153 offset:39680
	s_waitcnt lgkmcnt(9)
; #define LAS __attribute__((address_space(3)))
; DI unsigned pack2(float lo, float hi) { f32x2 v = {lo, hi}; return __builtin_bit_cast(unsigned, __builtin_convertvector(v, bf16x2_t)); }
; DI void scan_item(PP p, int l, int item, LAS unsigned char* lds) {
;     ...
;     for (int c = 0; c < NCH; ++c) {
;         if (wid >= 4) { if (c + 1 < NCH) { fill(c + 1); if (c + 2 < NCH) gl(c + 2); } }
;         else {
;             const LAS float* sp = buf + ((c & 1) * T) * 384;
;             f32x4 Ar0, Ar1, Aw0, Aw1, Ak0, Ak1, Aa0, Aa1, Ab0, Ab1; float Avv;
;             f32x4 Br0, Br1, Bw0, Bw1, Bk0, Bk1, Ba0, Ba1, Bb0, Bb1; float Bvv;
;             SC_LD(A, sp);
;             const ptrdiff_t ystep = dir ? -512 : 512;
;             u16* Yl = Yp + (size_t)steprow(b, dir, c * T) * 512 + (ptrdiff_t)ks * ystep;
; #pragma nounroll
;             for (int st = 0; st < T; st += 2) {
;                 SC_LD(B, sp + (st + 1) * 384);
;                 SC_STEP(A, st);
;                 if (st + 2 < T) SC_LD(A, sp + (st + 2) * 384);
;                 SC_STEP(B, st + 1);
;                 if ((st & 6) == 6) {
;                     const LAS float* rp = ypl + (ks * 68 - lane) + (lane & ~7);
;                     const f32x4 q0 = *(const LAS f32x4*)rp, q1 = *(const LAS f32x4*)(rp + 4);
;                     Yl[(ptrdiff_t)(st - 6) * ystep] = (u16)(pack2(((q0[0] + q0[1]) + (q0[2] + q0[3])) + ((q1[0] + q1[1]) + (q1[2] + q1[3])), 0.f) & 0xffffu);
;                 }
	v_pk_mul_f32 v[156:157], v[24:25], v[126:127]
	v_pk_fma_f32 v[126:127], v[116:117], v[16:17], v[126:127] op_sel_hi:[0,1,1]
	v_pk_fma_f32 v[156:157], v[124:125], v[26:27], v[156:157]
	v_pk_fma_f32 v[124:125], v[116:117], v[18:19], v[124:125] op_sel_hi:[0,1,1]
	v_pk_fma_f32 v[156:157], v[122:123], v[28:29], v[156:157]
	v_pk_fma_f32 v[122:123], v[116:117], v[20:21], v[122:123] op_sel_hi:[0,1,1]
	v_pk_fma_f32 v[156:157], v[120:121], v[30:31], v[156:157]
	v_pk_fma_f32 v[120:121], v[116:117], v[22:23], v[120:121] op_sel_hi:[0,1,1]
	v_add_f32_e32 v155, v156, v157
	s_nop 1
	v_add_f32_dpp v155, v155, v155 quad_perm:[1,0,3,2] row_mask:0xf bank_mask:0xf bound_ctrl:1
	s_nop 1
	v_add_f32_dpp v155, v155, v155 quad_perm:[2,3,0,1] row_mask:0xf bank_mask:0xf bound_ctrl:1
	s_nop 1
	v_add_f32_dpp v156, v155, v155 row_half_mirror row_mask:0xf bank_mask:0xf bound_ctrl:1
	v_pk_fma_f32 v[126:127], v[156:157], v[32:33], v[126:127] op_sel_hi:[0,1,1]
	v_pk_add_f32 v[82:83], v[82:83], v[84:85]
	v_pk_fma_f32 v[124:125], v[156:157], v[34:35], v[124:125] op_sel_hi:[0,1,1]
	v_pk_add_f32 v[86:87], v[86:87], v[88:89]
	v_pk_fma_f32 v[122:123], v[156:157], v[36:37], v[122:123] op_sel_hi:[0,1,1]
	v_pk_add_f32 v[82:83], v[82:83], v[86:87]
	v_pk_fma_f32 v[120:121], v[156:157], v[38:39], v[120:121] op_sel_hi:[0,1,1]
	v_add_f32_e32 v82, v82, v83
	v_cvt_pk_bf16_f32 v82, v82, v82
	global_store_short v[118:119], v82, off
	v_lshl_add_u64 v[118:119], s[8:9], 0, v[118:119]
	ds_read_b128 v[24:27], v154 offset:40704
	ds_read_b128 v[28:31], v154 offset:40720
	ds_read_b128 v[16:19], v154 offset:40448
	ds_read_b128 v[20:23], v154 offset:40464
	ds_read_b128 v[32:35], v154 offset:40960
	ds_read_b128 v[36:39], v154 offset:40976
	ds_read_b32 v116, v153 offset:41216
	s_waitcnt lgkmcnt(7)
	v_pk_mul_f32 v[158:159], v[0:1], v[126:127]
	v_pk_mul_f32 v[156:157], v[64:65], v[126:127]
	v_pk_fma_f32 v[158:159], v[124:125], v[2:3], v[158:159]
	v_pk_fma_f32 v[156:157], v[124:125], v[66:67], v[156:157]
	v_pk_fma_f32 v[126:127], v[128:129], v[56:57], v[126:127] op_sel_hi:[0,1,1]
	v_pk_fma_f32 v[158:159], v[122:123], v[4:5], v[158:159]
	v_pk_fma_f32 v[156:157], v[122:123], v[68:69], v[156:157]
	v_pk_fma_f32 v[124:125], v[128:129], v[58:59], v[124:125] op_sel_hi:[0,1,1]
	v_pk_fma_f32 v[158:159], v[120:121], v[6:7], v[158:159]
	v_pk_fma_f32 v[156:157], v[120:121], v[70:71], v[156:157]
	ds_read_b128 v[0:3], v154 offset:39936
	ds_read_b128 v[4:7], v154 offset:39952
	v_add_f32_e32 v155, v156, v157
	v_add_f32_e32 v158, v158, v159
	ds_write_b32 v137, v158 offset:0
	v_add_f32_dpp v155, v155, v155 quad_perm:[1,0,3,2] row_mask:0xf bank_mask:0xf bound_ctrl:1
	v_pk_fma_f32 v[122:123], v[128:129], v[60:61], v[122:123] op_sel_hi:[0,1,1]
	v_pk_fma_f32 v[120:121], v[128:129], v[62:63], v[120:121] op_sel_hi:[0,1,1]
	v_add_f32_dpp v155, v155, v155 quad_perm:[2,3,0,1] row_mask:0xf bank_mask:0xf bound_ctrl:1
	s_nop 1
	v_add_f32_dpp v156, v155, v155 row_half_mirror row_mask:0xf bank_mask:0xf bound_ctrl:1
	v_pk_fma_f32 v[126:127], v[156:157], v[72:73], v[126:127] op_sel_hi:[0,1,1]
	v_pk_fma_f32 v[124:125], v[156:157], v[74:75], v[124:125] op_sel_hi:[0,1,1]
	v_pk_fma_f32 v[122:123], v[156:157], v[76:77], v[122:123] op_sel_hi:[0,1,1]
	v_pk_fma_f32 v[120:121], v[156:157], v[78:79], v[120:121] op_sel_hi:[0,1,1]
	ds_read_b128 v[64:67], v154 offset:42240
	ds_read_b128 v[68:71], v154 offset:42256
	ds_read_b128 v[56:59], v154 offset:41984
	ds_read_b128 v[60:63], v154 offset:42000
	ds_read_b128 v[72:75], v154 offset:42496
	ds_read_b128 v[76:79], v154 offset:42512
	ds_read_b32 v128, v153 offset:42752
	s_waitcnt lgkmcnt(7)
	v_pk_mul_f32 v[158:159], v[40:41], v[126:127]
	v_pk_mul_f32 v[156:157], v[24:25], v[126:127]
	v_pk_fma_f32 v[158:159], v[124:125], v[42:43], v[158:159]
	v_pk_fma_f32 v[156:157], v[124:125], v[26:27], v[156:157]
	v_pk_fma_f32 v[126:127], v[116:117], v[16:17], v[126:127] op_sel_hi:[0,1,1]
	v_pk_fma_f32 v[158:159], v[122:123], v[44:45], v[158:159]
	v_pk_fma_f32 v[156:157], v[122:123], v[28:29], v[156:157]
	v_pk_fma_f32 v[124:125], v[116:117], v[18:19], v[124:125] op_sel_hi:[0,1,1]
	v_pk_fma_f32 v[158:159], v[120:121], v[46:47], v[158:159]
	v_pk_fma_f32 v[156:157], v[120:121], v[30:31], v[156:157]
	ds_read_b128 v[40:43], v154 offset:41472
	ds_read_b128 v[44:47], v154 offset:41488
	v_add_f32_e32 v155, v156, v157
	v_add_f32_e32 v158, v158, v159
	ds_write_b32 v137, v158 offset:272
	v_add_f32_dpp v155, v155, v155 quad_perm:[1,0,3,2] row_mask:0xf bank_mask:0xf bound_ctrl:1
	v_pk_fma_f32 v[122:123], v[116:117], v[20:21], v[122:123] op_sel_hi:[0,1,1]
	v_pk_fma_f32 v[120:121], v[116:117], v[22:23], v[120:121] op_sel_hi:[0,1,1]
	v_add_f32_dpp v155, v155, v155 quad_perm:[2,3,0,1] row_mask:0xf bank_mask:0xf bound_ctrl:1
	s_nop 1
	v_add_f32_dpp v156, v155, v155 row_half_mirror row_mask:0xf bank_mask:0xf bound_ctrl:1
	v_pk_fma_f32 v[126:127], v[156:157], v[32:33], v[126:127] op_sel_hi:[0,1,1]
	v_pk_fma_f32 v[124:125], v[156:157], v[34:35], v[124:125] op_sel_hi:[0,1,1]
	v_pk_fma_f32 v[122:123], v[156:157], v[36:37], v[122:123] op_sel_hi:[0,1,1]
	v_pk_fma_f32 v[120:121], v[156:157], v[38:39], v[120:121] op_sel_hi:[0,1,1]
	ds_read_b128 v[24:27], v154 offset:43776
	ds_read_b128 v[28:31], v154 offset:43792
	ds_read_b128 v[16:19], v154 offset:43520
	ds_read_b128 v[20:23], v154 offset:43536
	ds_read_b128 v[32:35], v154 offset:44032
	ds_read_b128 v[36:39], v154 offset:44048
	ds_read_b32 v116, v153 offset:44288
	s_waitcnt lgkmcnt(7)
; #define LAS __attribute__((address_space(3)))
; DI unsigned pack2(float lo, float hi) { f32x2 v = {lo, hi}; return __builtin_bit_cast(unsigned, __builtin_convertvector(v, bf16x2_t)); }
; DI void scan_item(PP p, int l, int item, LAS unsigned char* lds) {
;     ...
;     for (int c = 0; c < NCH; ++c) {
;         if (wid >= 4) { if (c + 1 < NCH) { fill(c + 1); if (c + 2 < NCH) gl(c + 2); } }
;         else {
;             const LAS float* sp = buf + ((c & 1) * T) * 384;
;             f32x4 Ar0, Ar1, Aw0, Aw1, Ak0, Ak1, Aa0, Aa1, Ab0, Ab1; float Avv;
;             f32x4 Br0, Br1, Bw0, Bw1, Bk0, Bk1, Ba0, Ba1, Bb0, Bb1; float Bvv;
;             SC_LD(A, sp);
;             const ptrdiff_t ystep = dir ? -512 : 512;
;             u16* Yl = Yp + (size_t)steprow(b, dir, c * T) * 512 + (ptrdiff_t)ks * ystep;
; #pragma nounroll
;             for (int st = 0; st < T; st += 2) {
;                 SC_LD(B, sp + (st + 1) * 384);
;                 SC_STEP(A, st);
;                 if (st + 2 < T) SC_LD(A, sp + (st + 2) * 384);
;                 SC_STEP(B, st + 1);
;                 if ((st & 6) == 6) {
;                     const LAS float* rp = ypl + (ks * 68 - lane) + (lane & ~7);
;                     const f32x4 q0 = *(const LAS f32x4*)rp, q1 = *(const LAS f32x4*)(rp + 4);
;                     Yl[(ptrdiff_t)(st - 6) * ystep] = (u16)(pack2(((q0[0] + q0[1]) + (q0[2] + q0[3])) + ((q1[0] + q1[1]) + (q1[2] + q1[3])), 0.f) & 0xffffu);
;                 }
	v_pk_mul_f32 v[158:159], v[0:1], v[126:127]
	v_pk_mul_f32 v[156:157], v[64:65], v[126:127]
	v_pk_fma_f32 v[158:159], v[124:125], v[2:3], v[158:159]
	v_pk_fma_f32 v[156:157], v[124:125], v[66:67], v[156:157]
	v_pk_fma_f32 v[126:127], v[128:129], v[56:57], v[126:127] op_sel_hi:[0,1,1]
	v_pk_fma_f32 v[158:159], v[122:123], v[4:5], v[158:159]
	v_pk_fma_f32 v[156:157], v[122:123], v[68:69], v[156:157]
	v_pk_fma_f32 v[124:125], v[128:129], v[58:59], v[124:125] op_sel_hi:[0,1,1]
	v_pk_fma_f32 v[158:159], v[120:121], v[6:7], v[158:159]
	v_pk_fma_f32 v[156:157], v[120:121], v[70:71], v[156:157]
	ds_read_b128 v[0:3], v154 offset:43008
	ds_read_b128 v[4:7], v154 offset:43024
	v_add_f32_e32 v155, v156, v157
	v_add_f32_e32 v158, v158, v159
	ds_write_b32 v137, v158 offset:544
	v_add_f32_dpp v155, v155, v155 quad_perm:[1,0,3,2] row_mask:0xf bank_mask:0xf bound_ctrl:1
	v_pk_fma_f32 v[122:123], v[128:129], v[60:61], v[122:123] op_sel_hi:[0,1,1]
	v_pk_fma_f32 v[120:121], v[128:129], v[62:63], v[120:121] op_sel_hi:[0,1,1]
	v_add_f32_dpp v155, v155, v155 quad_perm:[2,3,0,1] row_mask:0xf bank_mask:0xf bound_ctrl:1
	s_nop 1
	v_add_f32_dpp v156, v155, v155 row_half_mirror row_mask:0xf bank_mask:0xf bound_ctrl:1
	v_pk_fma_f32 v[126:127], v[156:157], v[72:73], v[126:127] op_sel_hi:[0,1,1]
	v_pk_fma_f32 v[124:125], v[156:157], v[74:75], v[124:125] op_sel_hi:[0,1,1]
	v_pk_fma_f32 v[122:123], v[156:157], v[76:77], v[122:123] op_sel_hi:[0,1,1]
	v_pk_fma_f32 v[120:121], v[156:157], v[78:79], v[120:121] op_sel_hi:[0,1,1]
	ds_read_b128 v[64:67], v154 offset:45312
	ds_read_b128 v[68:71], v154 offset:45328
	ds_read_b128 v[56:59], v154 offset:45056
	ds_read_b128 v[60:63], v154 offset:45072
	ds_read_b128 v[72:75], v154 offset:45568
	ds_read_b128 v[76:79], v154 offset:45584
	ds_read_b32 v128, v153 offset:45824
	s_waitcnt lgkmcnt(7)
	v_pk_mul_f32 v[158:159], v[40:41], v[126:127]
	v_pk_mul_f32 v[156:157], v[24:25], v[126:127]
	v_pk_fma_f32 v[158:159], v[124:125], v[42:43], v[158:159]
	v_pk_fma_f32 v[156:157], v[124:125], v[26:27], v[156:157]
	v_pk_fma_f32 v[126:127], v[116:117], v[16:17], v[126:127] op_sel_hi:[0,1,1]
	v_pk_fma_f32 v[158:159], v[122:123], v[44:45], v[158:159]
	v_pk_fma_f32 v[156:157], v[122:123], v[28:29], v[156:157]
	v_pk_fma_f32 v[124:125], v[116:117], v[18:19], v[124:125] op_sel_hi:[0,1,1]
	v_pk_fma_f32 v[158:159], v[120:121], v[46:47], v[158:159]
	v_pk_fma_f32 v[156:157], v[120:121], v[30:31], v[156:157]
	ds_read_b128 v[40:43], v154 offset:44544
	ds_read_b128 v[44:47], v154 offset:44560
	v_add_f32_e32 v155, v156, v157
	v_add_f32_e32 v158, v158, v159
	ds_write_b32 v137, v158 offset:816
	v_add_f32_dpp v155, v155, v155 quad_perm:[1,0,3,2] row_mask:0xf bank_mask:0xf bound_ctrl:1
	v_pk_fma_f32 v[122:123], v[116:117], v[20:21], v[122:123] op_sel_hi:[0,1,1]
	v_pk_fma_f32 v[120:121], v[116:117], v[22:23], v[120:121] op_sel_hi:[0,1,1]
	v_add_f32_dpp v155, v155, v155 quad_perm:[2,3,0,1] row_mask:0xf bank_mask:0xf bound_ctrl:1
	s_nop 1
	v_add_f32_dpp v156, v155, v155 row_half_mirror row_mask:0xf bank_mask:0xf bound_ctrl:1
	v_pk_fma_f32 v[126:127], v[156:157], v[32:33], v[126:127] op_sel_hi:[0,1,1]
	v_pk_fma_f32 v[124:125], v[156:157], v[34:35], v[124:125] op_sel_hi:[0,1,1]
	v_pk_fma_f32 v[122:123], v[156:157], v[36:37], v[122:123] op_sel_hi:[0,1,1]
	v_pk_fma_f32 v[120:121], v[156:157], v[38:39], v[120:121] op_sel_hi:[0,1,1]
	ds_read_b128 v[24:27], v154 offset:46848
	ds_read_b128 v[28:31], v154 offset:46864
	ds_read_b128 v[16:19], v154 offset:46592
	ds_read_b128 v[20:23], v154 offset:46608
	ds_read_b128 v[32:35], v154 offset:47104
	ds_read_b128 v[36:39], v154 offset:47120
	ds_read_b32 v116, v153 offset:47360
	s_waitcnt lgkmcnt(7)
	v_pk_mul_f32 v[158:159], v[0:1], v[126:127]
	v_pk_mul_f32 v[156:157], v[64:65], v[126:127]
	v_pk_fma_f32 v[158:159], v[124:125], v[2:3], v[158:159]
	v_pk_fma_f32 v[156:157], v[124:125], v[66:67], v[156:157]
	v_pk_fma_f32 v[126:127], v[128:129], v[56:57], v[126:127] op_sel_hi:[0,1,1]
	v_pk_fma_f32 v[158:159], v[122:123], v[4:5], v[158:159]
	v_pk_fma_f32 v[156:157], v[122:123], v[68:69], v[156:157]
	v_pk_fma_f32 v[124:125], v[128:129], v[58:59], v[124:125] op_sel_hi:[0,1,1]
	v_pk_fma_f32 v[158:159], v[120:121], v[6:7], v[158:159]
	v_pk_fma_f32 v[156:157], v[120:121], v[70:71], v[156:157]
	ds_read_b128 v[0:3], v154 offset:46080
	ds_read_b128 v[4:7], v154 offset:46096
	v_add_f32_e32 v155, v156, v157
	v_add_f32_e32 v158, v158, v159
	ds_write_b32 v137, v158 offset:1088
	v_add_f32_dpp v155, v155, v155 quad_perm:[1,0,3,2] row_mask:0xf bank_mask:0xf bound_ctrl:1
	v_pk_fma_f32 v[122:123], v[128:129], v[60:61], v[122:123] op_sel_hi:[0,1,1]
	v_pk_fma_f32 v[120:121], v[128:129], v[62:63], v[120:121] op_sel_hi:[0,1,1]
	v_add_f32_dpp v155, v155, v155 quad_perm:[2,3,0,1] row_mask:0xf bank_mask:0xf bound_ctrl:1
	s_nop 1
	v_add_f32_dpp v156, v155, v155 row_half_mirror row_mask:0xf bank_mask:0xf bound_ctrl:1
	v_pk_fma_f32 v[126:127], v[156:157], v[72:73], v[126:127] op_sel_hi:[0,1,1]
	v_pk_fma_f32 v[124:125], v[156:157], v[74:75], v[124:125] op_sel_hi:[0,1,1]
	v_pk_fma_f32 v[122:123], v[156:157], v[76:77], v[122:123] op_sel_hi:[0,1,1]
	v_pk_fma_f32 v[120:121], v[156:157], v[78:79], v[120:121] op_sel_hi:[0,1,1]
	ds_read_b128 v[64:67], v154 offset:48384
	ds_read_b128 v[68:71], v154 offset:48400
	ds_read_b128 v[56:59], v154 offset:48128
	ds_read_b128 v[60:63], v154 offset:48144
	ds_read_b128 v[72:75], v154 offset:48640
	ds_read_b128 v[76:79], v154 offset:48656
	ds_read_b32 v128, v153 offset:48896
	ds_read_b128 v[48:51], v154 offset:47872
	ds_read_b128 v[52:55], v154 offset:47888
	s_waitcnt lgkmcnt(9)
; #define LAS __attribute__((address_space(3)))
; DI unsigned pack2(float lo, float hi) { f32x2 v = {lo, hi}; return __builtin_bit_cast(unsigned, __builtin_convertvector(v, bf16x2_t)); }
; DI void scan_item(PP p, int l, int item, LAS unsigned char* lds) {
;     ...
;             for (int st = 0; st < T; st += 2) {
;                 SC_LD(B, sp + (st + 1) * 384);
;                 SC_STEP(A, st);
;                 if (st + 2 < T) SC_LD(A, sp + (st + 2) * 384);
;                 SC_STEP(B, st + 1);
;                 if ((st & 6) == 6) {
;                     const LAS float* rp = ypl + (ks * 68 - lane) + (lane & ~7);
;                     const f32x4 q0 = *(const LAS f32x4*)rp, q1 = *(const LAS f32x4*)(rp + 4);
;                     Yl[(ptrdiff_t)(st - 6) * ystep] = (u16)(pack2(((q0[0] + q0[1]) + (q0[2] + q0[3])) + ((q1[0] + q1[1]) + (q1[2] + q1[3])), 0.f) & 0xffffu);
;                 }
;             }
	v_pk_mul_f32 v[158:159], v[40:41], v[126:127]
	v_pk_mul_f32 v[156:157], v[24:25], v[126:127]
	v_pk_fma_f32 v[158:159], v[124:125], v[42:43], v[158:159]
	v_pk_fma_f32 v[156:157], v[124:125], v[26:27], v[156:157]
	v_pk_fma_f32 v[126:127], v[116:117], v[16:17], v[126:127] op_sel_hi:[0,1,1]
	v_pk_fma_f32 v[158:159], v[122:123], v[44:45], v[158:159]
	v_pk_fma_f32 v[156:157], v[122:123], v[28:29], v[156:157]
	v_pk_fma_f32 v[124:125], v[116:117], v[18:19], v[124:125] op_sel_hi:[0,1,1]
	v_pk_fma_f32 v[158:159], v[120:121], v[46:47], v[158:159]
	v_pk_fma_f32 v[156:157], v[120:121], v[30:31], v[156:157]
	ds_read_b128 v[40:43], v154 offset:47616
	ds_read_b128 v[44:47], v154 offset:47632
	v_add_f32_e32 v155, v156, v157
	v_add_f32_e32 v158, v158, v159
	ds_write_b32 v137, v158 offset:1360
	v_add_f32_dpp v155, v155, v155 quad_perm:[1,0,3,2] row_mask:0xf bank_mask:0xf bound_ctrl:1
	v_pk_fma_f32 v[122:123], v[116:117], v[20:21], v[122:123] op_sel_hi:[0,1,1]
	v_pk_fma_f32 v[120:121], v[116:117], v[22:23], v[120:121] op_sel_hi:[0,1,1]
	v_add_f32_dpp v155, v155, v155 quad_perm:[2,3,0,1] row_mask:0xf bank_mask:0xf bound_ctrl:1
	s_nop 1
	v_add_f32_dpp v156, v155, v155 row_half_mirror row_mask:0xf bank_mask:0xf bound_ctrl:1
	v_pk_fma_f32 v[126:127], v[156:157], v[32:33], v[126:127] op_sel_hi:[0,1,1]
	v_pk_fma_f32 v[124:125], v[156:157], v[34:35], v[124:125] op_sel_hi:[0,1,1]
	v_pk_fma_f32 v[122:123], v[156:157], v[36:37], v[122:123] op_sel_hi:[0,1,1]
	v_pk_fma_f32 v[120:121], v[156:157], v[38:39], v[120:121] op_sel_hi:[0,1,1]
	s_waitcnt lgkmcnt(0)
	v_pk_mul_f32 v[158:159], v[0:1], v[126:127]
	v_pk_mul_f32 v[156:157], v[64:65], v[126:127]
	v_pk_fma_f32 v[158:159], v[124:125], v[2:3], v[158:159]
	v_pk_fma_f32 v[156:157], v[124:125], v[66:67], v[156:157]
	v_pk_fma_f32 v[126:127], v[128:129], v[56:57], v[126:127] op_sel_hi:[0,1,1]
	v_pk_fma_f32 v[158:159], v[122:123], v[4:5], v[158:159]
	v_pk_fma_f32 v[156:157], v[122:123], v[68:69], v[156:157]
	v_pk_fma_f32 v[124:125], v[128:129], v[58:59], v[124:125] op_sel_hi:[0,1,1]
	v_pk_fma_f32 v[158:159], v[120:121], v[6:7], v[158:159]
	v_pk_fma_f32 v[156:157], v[120:121], v[70:71], v[156:157]
	s_nop 0
	v_add_f32_e32 v155, v156, v157
	v_add_f32_e32 v158, v158, v159
	ds_write_b32 v137, v158 offset:1632
	v_add_f32_dpp v155, v155, v155 quad_perm:[1,0,3,2] row_mask:0xf bank_mask:0xf bound_ctrl:1
	v_pk_fma_f32 v[122:123], v[128:129], v[60:61], v[122:123] op_sel_hi:[0,1,1]
	v_pk_fma_f32 v[120:121], v[128:129], v[62:63], v[120:121] op_sel_hi:[0,1,1]
	v_add_f32_dpp v155, v155, v155 quad_perm:[2,3,0,1] row_mask:0xf bank_mask:0xf bound_ctrl:1
	s_nop 1
	v_add_f32_dpp v156, v155, v155 row_half_mirror row_mask:0xf bank_mask:0xf bound_ctrl:1
	v_pk_fma_f32 v[126:127], v[156:157], v[72:73], v[126:127] op_sel_hi:[0,1,1]
	v_pk_fma_f32 v[124:125], v[156:157], v[74:75], v[124:125] op_sel_hi:[0,1,1]
	v_pk_fma_f32 v[122:123], v[156:157], v[76:77], v[122:123] op_sel_hi:[0,1,1]
	v_pk_fma_f32 v[120:121], v[156:157], v[78:79], v[120:121] op_sel_hi:[0,1,1]
	v_pk_mul_f32 v[158:159], v[40:41], v[126:127]
	s_nop 0
	v_pk_fma_f32 v[158:159], v[124:125], v[42:43], v[158:159]
	s_nop 0
	v_pk_fma_f32 v[158:159], v[122:123], v[44:45], v[158:159]
	s_nop 0
	v_pk_fma_f32 v[158:159], v[120:121], v[46:47], v[158:159]
	s_nop 0
	v_add_f32_e32 v158, v158, v159
	ds_write_b32 v137, v158 offset:1904
	ds_read_b128 v[82:85], v139
	ds_read_b128 v[86:89], v139 offset:16
	v_pk_mul_f32 v[126:127], v[48:49], v[126:127]
	v_pk_mul_f32 v[124:125], v[50:51], v[124:125]
	v_pk_mul_f32 v[122:123], v[52:53], v[122:123]
	v_pk_mul_f32 v[120:121], v[54:55], v[120:121]
	s_waitcnt lgkmcnt(0)
	v_pk_add_f32 v[82:83], v[82:83], v[84:85]
	v_pk_add_f32 v[86:87], v[86:87], v[88:89]
	s_nop 0
	v_pk_add_f32 v[82:83], v[82:83], v[86:87]
	s_nop 0
	v_add_f32_e32 v82, v82, v83
	v_cvt_pk_bf16_f32 v82, v82, v82
	global_store_short v[118:119], v82, off
	s_setprio 0

; #define LAS __attribute__((address_space(3)))
; DI void scan_item(PP p, int l, int item, LAS unsigned char* lds) {
;     ...
;     auto fill = [&](int c) {
;         const int pw = wid - 4;
;         float kk[8], n2[8];
; #pragma unroll
;         for (int i = 0; i < 8; ++i) { kk[i] = pk_[i] * kkw; n2[i] = kk[i] * kk[i]; }
; #pragma unroll
;         for (int i = 0; i < 8; ++i) n2[i] += dpp_f(n2[i], 0);
; #pragma unroll
;         for (int i = 0; i < 8; ++i) n2[i] += dpp_f(n2[i], 1);
; #pragma unroll
;         for (int i = 0; i < 8; ++i) n2[i] += dpp_f(n2[i], 2);
; #pragma unroll
;         for (int i = 0; i < 8; ++i) n2[i] += dpp_f(n2[i], 3);
; #pragma unroll
;         for (int i = 0; i < 8; ++i) n2[i] += __shfl_xor(n2[i], 16);
; #pragma unroll
;         for (int i = 0; i < 8; ++i) n2[i] += __shfl_xor(n2[i], 32);
; #pragma unroll
;         for (int i = 0; i < 8; ++i) {
;             const float kn = kk[i] * __builtin_amdgcn_rsqf(fmaxf(n2[i], 1e-24f));
;             LAS float* d = buf + ((c & 1) * T + pw * 8 + i) * 384 + lane;
;             d[0] = pr_[i]; d[64] = pd_[i]; d[128] = pk_[i] * (1.0f + (pa_[i] - 1.0f) * kaw); d[192] = -kn; d[256] = kn * pa_[i]; d[320] = pv_[i];
.LBB0_265:
	s_and_b64 vcc, exec, s[6:7]
	s_cbranch_vccz .LBB0_251
	s_cmpk_eq_i32 s30, 0x47
	s_cbranch_scc1 .LBB0_252
	s_waitcnt vmcnt(1)
	v_mul_f32_e32 v0, v117, v82
	v_mul_f32_e32 v1, v0, v0
	v_and_b32_e32 v17, 64, v185
	v_xor_b32_e32 v16, 16, v185
	v_mov_b32_dpp v1, v1 quad_perm:[1,0,3,2] row_mask:0xf bank_mask:0xf bound_ctrl:1
	v_fmac_f32_e32 v1, v0, v0
	v_add_u32_e32 v17, 64, v17
	v_cmp_lt_i32_e32 vcc, v16, v17
	v_add_f32_dpp v1, v1, v1 quad_perm:[2,3,0,1] row_mask:0xf bank_mask:0xf bound_ctrl:1
	v_mul_f32_e32 v2, v117, v83
	v_cndmask_b32_e32 v16, v185, v16, vcc
	v_add_f32_dpp v1, v1, v1 row_half_mirror row_mask:0xf bank_mask:0xf bound_ctrl:1
	v_mul_f32_e32 v3, v2, v2
	v_lshlrev_b32_e32 v16, 2, v16
	v_add_f32_dpp v1, v1, v1 row_mirror row_mask:0xf bank_mask:0xf bound_ctrl:1
	v_mov_b32_dpp v3, v3 quad_perm:[1,0,3,2] row_mask:0xf bank_mask:0xf bound_ctrl:1
	ds_bpermute_b32 v18, v16, v1
	v_fmac_f32_e32 v3, v2, v2
	v_mul_f32_e32 v4, v117, v90
	v_mul_f32_e32 v5, v4, v4
	v_add_f32_dpp v3, v3, v3 quad_perm:[2,3,0,1] row_mask:0xf bank_mask:0xf bound_ctrl:1
	s_waitcnt lgkmcnt(0)
	v_add_f32_e32 v1, v1, v18
	v_mov_b32_dpp v5, v5 quad_perm:[1,0,3,2] row_mask:0xf bank_mask:0xf bound_ctrl:1
	v_add_f32_dpp v3, v3, v3 row_half_mirror row_mask:0xf bank_mask:0xf bound_ctrl:1
	v_fmac_f32_e32 v5, v4, v4
	v_mul_f32_e32 v6, v117, v91
	v_add_f32_dpp v3, v3, v3 row_mirror row_mask:0xf bank_mask:0xf bound_ctrl:1
	ds_bpermute_b32 v18, v16, v3
	v_add_f32_dpp v5, v5, v5 quad_perm:[2,3,0,1] row_mask:0xf bank_mask:0xf bound_ctrl:1
	v_mul_f32_e32 v7, v6, v6
	v_mul_f32_e32 v8, v117, v98
	v_add_f32_dpp v5, v5, v5 row_half_mirror row_mask:0xf bank_mask:0xf bound_ctrl:1
	v_mov_b32_dpp v7, v7 quad_perm:[1,0,3,2] row_mask:0xf bank_mask:0xf bound_ctrl:1
	s_waitcnt lgkmcnt(0)
	v_add_f32_e32 v3, v3, v18
	v_add_f32_dpp v5, v5, v5 row_mirror row_mask:0xf bank_mask:0xf bound_ctrl:1
	ds_bpermute_b32 v18, v16, v5
	v_fmac_f32_e32 v7, v6, v6
	v_mul_f32_e32 v9, v8, v8
	v_mul_f32_e32 v10, v117, v99
	v_add_f32_dpp v7, v7, v7 quad_perm:[2,3,0,1] row_mask:0xf bank_mask:0xf bound_ctrl:1
	v_mov_b32_dpp v9, v9 quad_perm:[1,0,3,2] row_mask:0xf bank_mask:0xf bound_ctrl:1
	s_waitcnt lgkmcnt(0)
	v_add_f32_e32 v5, v5, v18
	v_add_f32_dpp v7, v7, v7 row_half_mirror row_mask:0xf bank_mask:0xf bound_ctrl:1
	v_fmac_f32_e32 v9, v8, v8
	v_mul_f32_e32 v11, v10, v10
	v_add_f32_dpp v7, v7, v7 row_mirror row_mask:0xf bank_mask:0xf bound_ctrl:1
	ds_bpermute_b32 v18, v16, v7
	v_add_f32_dpp v9, v9, v9 quad_perm:[2,3,0,1] row_mask:0xf bank_mask:0xf bound_ctrl:1
	v_mov_b32_dpp v11, v11 quad_perm:[1,0,3,2] row_mask:0xf bank_mask:0xf bound_ctrl:1
	v_fmac_f32_e32 v11, v10, v10
	v_add_f32_dpp v9, v9, v9 row_half_mirror row_mask:0xf bank_mask:0xf bound_ctrl:1
	s_waitcnt lgkmcnt(0)
	v_add_f32_e32 v7, v7, v18
	v_add_f32_dpp v11, v11, v11 quad_perm:[2,3,0,1] row_mask:0xf bank_mask:0xf bound_ctrl:1
	v_add_f32_dpp v9, v9, v9 row_mirror row_mask:0xf bank_mask:0xf bound_ctrl:1
	ds_bpermute_b32 v18, v16, v9
	v_mul_f32_e32 v12, v117, v106
	v_mul_f32_e32 v14, v117, v107
	v_add_f32_dpp v11, v11, v11 row_half_mirror row_mask:0xf bank_mask:0xf bound_ctrl:1
	v_mul_f32_e32 v13, v12, v12
	v_mul_f32_e32 v15, v14, v14
	v_add_f32_dpp v11, v11, v11 row_mirror row_mask:0xf bank_mask:0xf bound_ctrl:1
	v_mov_b32_dpp v13, v13 quad_perm:[1,0,3,2] row_mask:0xf bank_mask:0xf bound_ctrl:1
	v_mov_b32_dpp v15, v15 quad_perm:[1,0,3,2] row_mask:0xf bank_mask:0xf bound_ctrl:1
	s_waitcnt lgkmcnt(0)
	v_add_f32_e32 v9, v9, v18
	ds_bpermute_b32 v18, v16, v11
	v_fmac_f32_e32 v13, v12, v12
	v_fmac_f32_e32 v15, v14, v14
	s_lshl_b32 s6, s30, 31
	v_add_f32_dpp v13, v13, v13 quad_perm:[2,3,0,1] row_mask:0xf bank_mask:0xf bound_ctrl:1
	v_add_f32_dpp v15, v15, v15 quad_perm:[2,3,0,1] row_mask:0xf bank_mask:0xf bound_ctrl:1
	s_waitcnt lgkmcnt(0)
	v_add_f32_e32 v11, v11, v18
	v_add_f32_dpp v13, v13, v13 row_half_mirror row_mask:0xf bank_mask:0xf bound_ctrl:1
	v_add_f32_dpp v15, v15, v15 row_half_mirror row_mask:0xf bank_mask:0xf bound_ctrl:1
	s_ashr_i32 s6, s6, 26
	v_add_f32_dpp v13, v13, v13 row_mirror row_mask:0xf bank_mask:0xf bound_ctrl:1
	v_add_f32_dpp v15, v15, v15 row_mirror row_mask:0xf bank_mask:0xf bound_ctrl:1
	ds_bpermute_b32 v18, v16, v13
	ds_bpermute_b32 v16, v16, v15
	s_add_i32 s6, s6, s52
	s_mulk_i32 s6, 0x600
	s_cmpk_gt_u32 s30, 0x45
	s_waitcnt lgkmcnt(1)
	v_add_f32_e32 v13, v13, v18
	s_waitcnt lgkmcnt(0)
	v_add_f32_e32 v15, v15, v16
	v_xor_b32_e32 v16, 32, v185
	v_cmp_lt_i32_e32 vcc, v16, v17
	s_nop 1
	v_cndmask_b32_e32 v16, v185, v16, vcc
	v_lshlrev_b32_e32 v16, 2, v16
	ds_bpermute_b32 v17, v16, v1
	s_waitcnt lgkmcnt(0)
	v_add_f32_e32 v1, v1, v17
	ds_bpermute_b32 v17, v16, v3
	v_max_f32_e32 v1, 0x179abe15, v1
	v_rsq_f32_e32 v1, v1
	s_waitcnt lgkmcnt(0)
	v_add_f32_e32 v3, v3, v17
	ds_bpermute_b32 v17, v16, v5
	v_mul_f32_e64 v0, v0, -v1
	v_add_f32_e32 v1, -1.0, v88
	s_waitcnt vmcnt(0)
	v_fma_f32 v1, v129, v1, 1.0
	v_mul_f32_e32 v1, v83, v1
	s_waitcnt lgkmcnt(0)
	v_add_f32_e32 v5, v5, v17
	ds_bpermute_b32 v17, v16, v7
	s_waitcnt lgkmcnt(0)
	v_add_f32_e32 v7, v7, v17
	ds_bpermute_b32 v17, v16, v9
	s_waitcnt lgkmcnt(0)
	v_add_f32_e32 v9, v9, v17
	ds_bpermute_b32 v17, v16, v11
	s_waitcnt lgkmcnt(0)
	v_add_f32_e32 v11, v11, v17
	ds_bpermute_b32 v17, v16, v13
	ds_bpermute_b32 v16, v16, v15
	s_waitcnt lgkmcnt(1)
	v_add_f32_e32 v13, v13, v17
	v_add_f32_e32 v17, -1.0, v89
	v_fma_f32 v17, v129, v17, 1.0
	s_waitcnt lgkmcnt(0)
; #define LAS __attribute__((address_space(3)))
; DI void scan_item(PP p, int l, int item, LAS unsigned char* lds) {
;     ...
; #pragma unroll
;         for (int i = 0; i < 8; ++i) {
;             const float kn = kk[i] * __builtin_amdgcn_rsqf(fmaxf(n2[i], 1e-24f));
;             LAS float* d = buf + ((c & 1) * T + pw * 8 + i) * 384 + lane;
;             d[0] = pr_[i]; d[64] = pd_[i]; d[128] = pk_[i] * (1.0f + (pa_[i] - 1.0f) * kaw); d[192] = -kn; d[256] = kn * pa_[i]; d[320] = pv_[i];
;         }
	v_add_f32_e32 v15, v15, v16
	v_add_u32_e32 v16, s6, v140
	v_mul_f32_e32 v17, v82, v17
	ds_write2st64_b32 v16, v17, v0 offset0:2 offset1:3
	v_mul_f32_e64 v0, v89, -v0
	ds_write2st64_b32 v16, v0, v87 offset0:4 offset1:5
	v_max_f32_e32 v0, 0x179abe15, v3
	v_rsq_f32_e32 v0, v0
	ds_write2st64_b32 v16, v85, v130 offset1:1
	ds_write2st64_b32 v16, v84, v131 offset0:6 offset1:7
	ds_write2st64_b32 v16, v93, v132 offset0:12 offset1:13
	v_mul_f32_e64 v0, v2, -v0
	ds_write2st64_b32 v16, v1, v0 offset0:8 offset1:9
	v_mul_f32_e64 v0, v88, -v0
	ds_write2st64_b32 v16, v0, v86 offset0:10 offset1:11
	v_max_f32_e32 v0, 0x179abe15, v5
	v_rsq_f32_e32 v0, v0
	v_add_f32_e32 v1, -1.0, v101
	v_fma_f32 v1, v129, v1, 1.0
	v_mul_f32_e32 v1, v90, v1
	v_mul_f32_e64 v0, v4, -v0
	ds_write2st64_b32 v16, v1, v0 offset0:14 offset1:15
	v_mul_f32_e64 v0, v101, -v0
	ds_write2st64_b32 v16, v0, v95 offset0:16 offset1:17
	v_max_f32_e32 v0, 0x179abe15, v7
	v_rsq_f32_e32 v0, v0
	v_add_f32_e32 v1, -1.0, v100
	v_fma_f32 v1, v129, v1, 1.0
	v_mul_f32_e32 v1, v91, v1
	v_mul_f32_e64 v0, v6, -v0
	ds_write2st64_b32 v16, v1, v0 offset0:20 offset1:21
	v_mul_f32_e64 v0, v100, -v0
	ds_write2st64_b32 v16, v0, v94 offset0:22 offset1:23
	v_max_f32_e32 v0, 0x179abe15, v9
	v_rsq_f32_e32 v0, v0
	v_add_f32_e32 v1, -1.0, v109
	v_fma_f32 v1, v129, v1, 1.0
	v_mul_f32_e32 v1, v98, v1
	v_mul_f32_e64 v0, v8, -v0
	ds_write2st64_b32 v16, v1, v0 offset0:26 offset1:27
	v_mul_f32_e64 v0, v109, -v0
	ds_write2st64_b32 v16, v0, v105 offset0:28 offset1:29
	v_max_f32_e32 v0, 0x179abe15, v11
	v_rsq_f32_e32 v0, v0
	v_add_f32_e32 v1, -1.0, v108
	v_fma_f32 v1, v129, v1, 1.0
	v_mul_f32_e32 v1, v99, v1
	v_mul_f32_e64 v0, v10, -v0
	ds_write2st64_b32 v16, v1, v0 offset0:32 offset1:33
	v_mul_f32_e64 v0, v108, -v0
	ds_write2st64_b32 v16, v0, v104 offset0:34 offset1:35
	v_max_f32_e32 v0, 0x179abe15, v13
	v_rsq_f32_e32 v0, v0
	v_add_f32_e32 v1, -1.0, v115
	v_fma_f32 v1, v129, v1, 1.0
	v_mul_f32_e32 v1, v106, v1
	v_mul_f32_e64 v0, v12, -v0
	ds_write2st64_b32 v16, v1, v0 offset0:38 offset1:39
	v_mul_f32_e64 v0, v115, -v0
	ds_write2st64_b32 v16, v0, v113 offset0:40 offset1:41
	v_max_f32_e32 v0, 0x179abe15, v15
	v_rsq_f32_e32 v0, v0
	v_add_f32_e32 v1, -1.0, v114
	v_fma_f32 v1, v129, v1, 1.0
	v_mul_f32_e32 v1, v107, v1
	v_mul_f32_e64 v0, v14, -v0
	ds_write2st64_b32 v16, v1, v0 offset0:44 offset1:45
	v_mul_f32_e64 v0, v114, -v0
	ds_write2st64_b32 v16, v92, v133 offset0:18 offset1:19
	ds_write2st64_b32 v16, v103, v134 offset0:24 offset1:25
	ds_write2st64_b32 v16, v102, v135 offset0:30 offset1:31
	ds_write2st64_b32 v16, v111, v141 offset0:36 offset1:37
	ds_write2st64_b32 v16, v110, v152 offset0:42 offset1:43
	ds_write2st64_b32 v16, v0, v112 offset0:46 offset1:47
	v_mov_b32_e32 v153, 1.0
	ds_read_b32 v118, v16 offset:0
	ds_read_b32 v122, v16 offset:256
	ds_read_b32 v126, v16 offset:512
	ds_read_b32 v144, v16 offset:768
	ds_read_b32 v148, v16 offset:1024
	ds_read_b32 v119, v16 offset:1536
	ds_read_b32 v123, v16 offset:1792
	ds_read_b32 v127, v16 offset:2048
	ds_read_b32 v145, v16 offset:2304
	ds_read_b32 v149, v16 offset:2560
	ds_read_b32 v120, v16 offset:3072
	ds_read_b32 v124, v16 offset:3328
	ds_read_b32 v128, v16 offset:3584
	ds_read_b32 v146, v16 offset:3840
	ds_read_b32 v150, v16 offset:4096
	ds_read_b32 v121, v16 offset:4608
	ds_read_b32 v125, v16 offset:4864
	ds_read_b32 v116, v16 offset:5120
	ds_read_b32 v147, v16 offset:5376
	ds_read_b32 v151, v16 offset:5632
	s_waitcnt lgkmcnt(0)
	v_mul_f32_e32 v144, v144, v153
	v_mul_f32_e32 v153, v153, v122
	v_rcp_f32_e32 v154, v153
	v_mul_f32_e32 v118, v118, v153
	v_mov_b32_e32 v122, v153
	v_mul_f32_e32 v126, v126, v154
	v_mul_f32_e32 v148, v148, v154
	v_mul_f32_e32 v145, v145, v153
	v_mul_f32_e32 v153, v153, v123
	v_rcp_f32_e32 v155, v153
	v_mul_f32_e32 v119, v119, v153
	v_mov_b32_e32 v123, v153
	v_mul_f32_e32 v127, v127, v155
	v_mul_f32_e32 v149, v149, v155
	v_mul_f32_e32 v146, v146, v153
	v_mul_f32_e32 v153, v153, v124
	v_rcp_f32_e32 v156, v153
	v_mul_f32_e32 v120, v120, v153
	v_mov_b32_e32 v124, v153
	v_mul_f32_e32 v128, v128, v156
	v_mul_f32_e32 v150, v150, v156
	v_mul_f32_e32 v147, v147, v153
	v_mul_f32_e32 v153, v153, v125
	v_rcp_f32_e32 v157, v153
	v_mul_f32_e32 v121, v121, v153
	v_mov_b32_e32 v125, v153
	v_mul_f32_e32 v116, v116, v157
	v_mul_f32_e32 v151, v151, v157
	ds_write_b32 v16, v118 offset:0
	ds_write_b32 v16, v122 offset:256
	ds_write_b32 v16, v126 offset:512
	ds_write_b32 v16, v144 offset:768
	ds_write_b32 v16, v148 offset:1024
	ds_write_b32 v16, v119 offset:1536
	ds_write_b32 v16, v123 offset:1792
	ds_write_b32 v16, v127 offset:2048
	ds_write_b32 v16, v145 offset:2304
	ds_write_b32 v16, v149 offset:2560
	ds_write_b32 v16, v120 offset:3072
	ds_write_b32 v16, v124 offset:3328
	ds_write_b32 v16, v128 offset:3584
	ds_write_b32 v16, v146 offset:3840
	ds_write_b32 v16, v150 offset:4096
	ds_write_b32 v16, v121 offset:4608
	ds_write_b32 v16, v125 offset:4864
	ds_write_b32 v16, v116 offset:5120
	ds_write_b32 v16, v147 offset:5376
	ds_write_b32 v16, v151 offset:5632
	ds_read_b32 v118, v16 offset:6144
	ds_read_b32 v122, v16 offset:6400
	ds_read_b32 v126, v16 offset:6656
	ds_read_b32 v144, v16 offset:6912
	ds_read_b32 v148, v16 offset:7168
	ds_read_b32 v119, v16 offset:7680
	ds_read_b32 v123, v16 offset:7936
	ds_read_b32 v127, v16 offset:8192
	ds_read_b32 v145, v16 offset:8448
	ds_read_b32 v149, v16 offset:8704
	ds_read_b32 v120, v16 offset:9216
	ds_read_b32 v124, v16 offset:9472
	ds_read_b32 v128, v16 offset:9728
	ds_read_b32 v146, v16 offset:9984
	ds_read_b32 v150, v16 offset:10240
	ds_read_b32 v121, v16 offset:10752
	ds_read_b32 v125, v16 offset:11008
	ds_read_b32 v116, v16 offset:11264
	ds_read_b32 v147, v16 offset:11520
	ds_read_b32 v151, v16 offset:11776
	s_waitcnt lgkmcnt(0)
; DI float bf2f(u16 b) { return __uint_as_float(((unsigned)b) << 16); }
; DI void scan_item(PP p, int l, int item, LAS unsigned char* lds) {
;     ...
;     auto gl = [&](int c) {
;         const int pw = wid - 4;
;         const int row0 = steprow(b, dir, c * T + pw * 8); const int rs = dir ? -1 : 1;
; #pragma unroll
;         for (int i = 0; i < 8; ++i) { const size_t o = (size_t)(row0 + rs * i) * 512 + ch;
;             pr_[i] = bf2f(RKV[o]); pk_[i] = bf2f(RKV[(size_t)NTOK * 512 + o]); pv_[i] = bf2f(RKV[(size_t)2 * NTOK * 512 + o]); pd_[i] = DEC[o]; pa_[i] = bf2f(AA[o]); }
;     };
;     ...
;         if (wid >= 4) { if (c + 1 < NCH) { fill(c + 1); if (c + 2 < NCH) gl(c + 2); } }
	v_mul_f32_e32 v144, v144, v153
	v_mul_f32_e32 v153, v153, v122
	v_rcp_f32_e32 v154, v153
	v_mul_f32_e32 v118, v118, v153
	v_mov_b32_e32 v122, v153
	v_mul_f32_e32 v126, v126, v154
	v_mul_f32_e32 v148, v148, v154
	v_mul_f32_e32 v145, v145, v153
	v_mul_f32_e32 v153, v153, v123
	v_rcp_f32_e32 v155, v153
	v_mul_f32_e32 v119, v119, v153
	v_mov_b32_e32 v123, v153
	v_mul_f32_e32 v127, v127, v155
	v_mul_f32_e32 v149, v149, v155
	v_mul_f32_e32 v146, v146, v153
	v_mul_f32_e32 v153, v153, v124
	v_rcp_f32_e32 v156, v153
	v_mul_f32_e32 v120, v120, v153
	v_mov_b32_e32 v124, v153
	v_mul_f32_e32 v128, v128, v156
	v_mul_f32_e32 v150, v150, v156
	v_mul_f32_e32 v147, v147, v153
	v_mul_f32_e32 v153, v153, v125
	v_rcp_f32_e32 v157, v153
	v_mul_f32_e32 v121, v121, v153
	v_mov_b32_e32 v125, v153
	v_mul_f32_e32 v116, v116, v157
	v_mul_f32_e32 v151, v151, v157
	ds_write_b32 v16, v118 offset:6144
	ds_write_b32 v16, v122 offset:6400
	ds_write_b32 v16, v126 offset:6656
	ds_write_b32 v16, v144 offset:6912
	ds_write_b32 v16, v148 offset:7168
	ds_write_b32 v16, v119 offset:7680
	ds_write_b32 v16, v123 offset:7936
	ds_write_b32 v16, v127 offset:8192
	ds_write_b32 v16, v145 offset:8448
	ds_write_b32 v16, v149 offset:8704
	ds_write_b32 v16, v120 offset:9216
	ds_write_b32 v16, v124 offset:9472
	ds_write_b32 v16, v128 offset:9728
	ds_write_b32 v16, v146 offset:9984
	ds_write_b32 v16, v150 offset:10240
	ds_write_b32 v16, v121 offset:10752
	ds_write_b32 v16, v125 offset:11008
	ds_write_b32 v16, v116 offset:11264
	ds_write_b32 v16, v147 offset:11520
	ds_write_b32 v16, v151 offset:11776
	s_cbranch_scc1 .LBB0_252
	s_lshl_b32 s6, s30, 5
	s_add_i32 s6, s54, s6
	s_add_i32 s7, s6, 0xffffff00
	s_cmpk_lt_i32 s6, 0x100
	s_movk_i32 s3, 0x8ff
	s_cselect_b32 s8, 0xff, s3
	s_cselect_b32 s9, s6, s7
	s_cselect_b32 s68, s24, s53
	s_sub_i32 s8, s8, s6
	s_and_b64 s[6:7], s[46:47], exec
	s_cselect_b32 s6, s9, s8
	s_add_i32 s6, s6, s68
	s_ashr_i32 s7, s6, 31
	s_lshl_b64 s[8:9], s[6:7], 9
	v_lshl_add_u64 v[0:1], s[8:9], 0, v[96:97]
	s_add_i32 s8, s6, s55
	s_ashr_i32 s9, s8, 31
	v_lshlrev_b64 v[2:3], 1, v[0:1]
	s_lshl_b64 s[8:9], s[8:9], 9
	v_lshl_add_u64 v[4:5], s[4:5], 0, v[2:3]
	s_mov_b32 s68, 0x1200000
	v_lshl_add_u64 v[8:9], s[8:9], 0, v[96:97]
	v_add_co_u32_e32 v6, vcc, s68, v4
	v_lshlrev_b64 v[10:11], 1, v[8:9]
	s_nop 0
	v_addc_co_u32_e32 v7, vcc, 0, v5, vcc
	v_lshl_add_u64 v[12:13], s[4:5], 0, v[10:11]
	v_add_co_u32_e32 v14, vcc, s68, v12
	s_mov_b32 s3, 0x2400000
	s_nop 0
	v_addc_co_u32_e32 v15, vcc, 0, v13, vcc
	v_add_co_u32_e32 v16, vcc, s3, v12
	s_add_i32 s8, s6, s56
	s_nop 0
	v_addc_co_u32_e32 v17, vcc, 0, v13, vcc
	s_ashr_i32 s9, s8, 31
	v_add_co_u32_e32 v18, vcc, s3, v4
	s_lshl_b64 s[8:9], s[8:9], 9
	v_lshl_add_u64 v[0:1], v[0:1], 2, s[36:37]
	v_lshl_add_u64 v[2:3], s[42:43], 0, v[2:3]
	v_addc_co_u32_e32 v19, vcc, 0, v5, vcc
	global_load_ushort v26, v[6:7], off
	global_load_dword v130, v[0:1], off
	global_load_ushort v27, v[12:13], off
	global_load_ushort v28, v[14:15], off
	global_load_ushort v29, v[16:17], off
	global_load_ushort v30, v[18:19], off
	global_load_ushort v31, v[2:3], off
	global_load_ushort v32, v[4:5], off
	v_lshl_add_u64 v[4:5], s[8:9], 0, v[96:97]
	s_add_i32 s8, s6, s57
	s_ashr_i32 s9, s8, 31
	v_lshlrev_b64 v[6:7], 1, v[4:5]
	s_lshl_b64 s[8:9], s[8:9], 9
	v_lshl_add_u64 v[0:1], v[8:9], 2, s[36:37]
	v_lshl_add_u64 v[8:9], s[4:5], 0, v[6:7]
	v_lshl_add_u64 v[12:13], s[8:9], 0, v[96:97]
	v_lshl_add_u64 v[2:3], s[42:43], 0, v[10:11]
	v_add_co_u32_e32 v10, vcc, s68, v8
	v_lshlrev_b64 v[14:15], 1, v[12:13]
	s_nop 0
	v_addc_co_u32_e32 v11, vcc, 0, v9, vcc
	v_lshl_add_u64 v[16:17], s[4:5], 0, v[14:15]
	v_add_co_u32_e32 v18, vcc, s68, v16
	v_lshl_add_u64 v[4:5], v[4:5], 2, s[36:37]
	s_nop 0
	v_addc_co_u32_e32 v19, vcc, 0, v17, vcc
	v_lshl_add_u64 v[6:7], s[42:43], 0, v[6:7]
	global_load_dword v131, v[0:1], off
	global_load_ushort v33, v[2:3], off
	global_load_ushort v34, v[10:11], off
	global_load_dword v132, v[4:5], off
	global_load_ushort v35, v[16:17], off
	global_load_ushort v36, v[18:19], off
	global_load_ushort v37, v[6:7], off
	global_load_ushort v38, v[8:9], off
	v_add_co_u32_e32 v0, vcc, s3, v16
	s_add_i32 s8, s6, s58
	s_nop 0
	v_addc_co_u32_e32 v1, vcc, 0, v17, vcc
	s_ashr_i32 s9, s8, 31
	v_add_co_u32_e32 v2, vcc, s3, v8
	s_lshl_b64 s[8:9], s[8:9], 9
	s_nop 0
	v_addc_co_u32_e32 v3, vcc, 0, v9, vcc
; DI float bf2f(u16 b) { return __uint_as_float(((unsigned)b) << 16); }
; DI void scan_item(PP p, int l, int item, LAS unsigned char* lds) {
;     ...
;     auto gl = [&](int c) {
;         const int pw = wid - 4;
;         const int row0 = steprow(b, dir, c * T + pw * 8); const int rs = dir ? -1 : 1;
; #pragma unroll
;         for (int i = 0; i < 8; ++i) { const size_t o = (size_t)(row0 + rs * i) * 512 + ch;
;             pr_[i] = bf2f(RKV[o]); pk_[i] = bf2f(RKV[(size_t)NTOK * 512 + o]); pv_[i] = bf2f(RKV[(size_t)2 * NTOK * 512 + o]); pd_[i] = DEC[o]; pa_[i] = bf2f(AA[o]); }
;     };
	v_lshl_add_u64 v[8:9], s[8:9], 0, v[96:97]
	s_add_i32 s8, s6, s59
	s_ashr_i32 s9, s8, 31
	v_lshlrev_b64 v[10:11], 1, v[8:9]
	s_lshl_b64 s[8:9], s[8:9], 9
	v_lshl_add_u64 v[4:5], v[12:13], 2, s[36:37]
	v_lshl_add_u64 v[12:13], s[4:5], 0, v[10:11]
	v_lshl_add_u64 v[16:17], s[8:9], 0, v[96:97]
	v_lshl_add_u64 v[6:7], s[42:43], 0, v[14:15]
	v_add_co_u32_e32 v14, vcc, s68, v12
	v_lshlrev_b64 v[18:19], 1, v[16:17]
	s_nop 0
	v_addc_co_u32_e32 v15, vcc, 0, v13, vcc
	v_lshl_add_u64 v[20:21], s[4:5], 0, v[18:19]
	v_lshl_add_u64 v[8:9], v[8:9], 2, s[36:37]
	v_lshl_add_u64 v[10:11], s[42:43], 0, v[10:11]
	global_load_ushort v39, v[0:1], off
	global_load_ushort v40, v[2:3], off
	global_load_dword v133, v[4:5], off
	global_load_ushort v41, v[6:7], off
	global_load_ushort v42, v[14:15], off
	global_load_dword v134, v[8:9], off
	global_load_ushort v43, v[10:11], off
	global_load_ushort v44, v[12:13], off
	v_add_co_u32_e32 v0, vcc, s68, v20
	s_add_i32 s8, s6, s60
	s_nop 0
	v_addc_co_u32_e32 v1, vcc, 0, v21, vcc
	v_add_co_u32_e32 v2, vcc, s3, v20
	s_ashr_i32 s9, s8, 31
	s_nop 0
	v_addc_co_u32_e32 v3, vcc, 0, v21, vcc
	s_lshl_b64 s[8:9], s[8:9], 9
	s_add_i32 s6, s6, s61
	v_add_co_u32_e32 v4, vcc, s3, v12
	v_lshl_add_u64 v[10:11], s[8:9], 0, v[96:97]
	s_ashr_i32 s7, s6, 31
	v_addc_co_u32_e32 v5, vcc, 0, v13, vcc
	v_lshlrev_b64 v[12:13], 1, v[10:11]
	s_lshl_b64 s[6:7], s[6:7], 9
	v_lshl_add_u64 v[8:9], s[42:43], 0, v[18:19]
	v_lshl_add_u64 v[14:15], s[4:5], 0, v[12:13]
	v_lshl_add_u64 v[18:19], s[6:7], 0, v[96:97]
	v_lshl_add_u64 v[6:7], v[16:17], 2, s[36:37]
	v_add_co_u32_e32 v16, vcc, s68, v14
	v_lshlrev_b64 v[22:23], 1, v[18:19]
	s_nop 0
	v_addc_co_u32_e32 v17, vcc, 0, v15, vcc
	v_lshl_add_u64 v[24:25], s[4:5], 0, v[22:23]
	global_load_ushort v20, v[20:21], off
	s_nop 0
	global_load_ushort v21, v[0:1], off
	global_load_ushort v45, v[2:3], off
	global_load_ushort v46, v[4:5], off
	global_load_dword v135, v[6:7], off
	global_load_ushort v47, v[8:9], off
	s_nop 0
	global_load_ushort v16, v[16:17], off
	s_nop 0
	global_load_ushort v17, v[14:15], off
	v_add_co_u32_e32 v0, vcc, s68, v24
	v_lshl_add_u64 v[12:13], s[42:43], 0, v[12:13]
	s_nop 0
	v_addc_co_u32_e32 v1, vcc, 0, v25, vcc
	v_add_co_u32_e32 v2, vcc, s3, v24
	v_lshl_add_u64 v[6:7], v[18:19], 2, s[36:37]
	s_nop 0
	v_addc_co_u32_e32 v3, vcc, 0, v25, vcc
	v_add_co_u32_e32 v4, vcc, s3, v14
	v_lshl_add_u64 v[8:9], s[42:43], 0, v[22:23]
	s_nop 0
	v_addc_co_u32_e32 v5, vcc, 0, v15, vcc
	global_load_ushort v14, v[24:25], off
	global_load_ushort v15, v[0:1], off
	s_nop 0
	global_load_ushort v2, v[2:3], off
	s_nop 0
	global_load_ushort v3, v[4:5], off
	global_load_dword v152, v[6:7], off
	s_nop 0
	global_load_ushort v4, v[8:9], off
	global_load_ushort v5, v[12:13], off
	v_lshl_add_u64 v[0:1], v[10:11], 2, s[36:37]
	global_load_dword v141, v[0:1], off
	s_waitcnt vmcnt(32)
	v_lshlrev_b32_e32 v85, 16, v32
	v_lshlrev_b32_e32 v84, 16, v27
	v_lshlrev_b32_e32 v82, 16, v26
	v_lshlrev_b32_e32 v83, 16, v28
	v_lshlrev_b32_e32 v87, 16, v30
	v_lshlrev_b32_e32 v86, 16, v29
	v_lshlrev_b32_e32 v89, 16, v31
	s_waitcnt vmcnt(30)
	v_lshlrev_b32_e32 v88, 16, v33
	s_waitcnt vmcnt(24)
	v_lshlrev_b32_e32 v93, 16, v38
	v_lshlrev_b32_e32 v92, 16, v35
	v_lshlrev_b32_e32 v91, 16, v36
	v_lshlrev_b32_e32 v90, 16, v34
	v_lshlrev_b32_e32 v101, 16, v37
	s_waitcnt vmcnt(23)
	v_lshlrev_b32_e32 v94, 16, v39
	s_waitcnt vmcnt(22)
	v_lshlrev_b32_e32 v95, 16, v40
	s_waitcnt vmcnt(20)
	v_lshlrev_b32_e32 v100, 16, v41
	s_waitcnt vmcnt(19)
	v_lshlrev_b32_e32 v98, 16, v42
	s_waitcnt vmcnt(17)
	v_lshlrev_b32_e32 v109, 16, v43
	s_waitcnt vmcnt(16)
	v_lshlrev_b32_e32 v103, 16, v44
	s_waitcnt vmcnt(15)
	v_lshlrev_b32_e32 v102, 16, v20
	s_waitcnt vmcnt(14)
	v_lshlrev_b32_e32 v99, 16, v21
	s_waitcnt vmcnt(13)
	v_lshlrev_b32_e32 v104, 16, v45
	s_waitcnt vmcnt(12)
	v_lshlrev_b32_e32 v105, 16, v46
	s_waitcnt vmcnt(10)
	v_lshlrev_b32_e32 v108, 16, v47
	s_waitcnt vmcnt(9)
	v_lshlrev_b32_e32 v106, 16, v16
	s_waitcnt vmcnt(8)
	v_lshlrev_b32_e32 v111, 16, v17
	s_waitcnt vmcnt(7)
	v_lshlrev_b32_e32 v110, 16, v14
	s_waitcnt vmcnt(6)
	v_lshlrev_b32_e32 v107, 16, v15
	s_waitcnt vmcnt(5)
	v_lshlrev_b32_e32 v112, 16, v2
	s_waitcnt vmcnt(4)
	v_lshlrev_b32_e32 v113, 16, v3
	s_waitcnt vmcnt(2)
	v_lshlrev_b32_e32 v114, 16, v4
	s_waitcnt vmcnt(1)
	v_lshlrev_b32_e32 v115, 16, v5
	s_branch .LBB0_252
